# attention on 16x16x32 MFMA: S^T blocks reused in place as PV A operand, plain-row V image, own epilogue; dead g-max scan loop removed
# speedup vs baseline: 1.0516x; 1.0150x over previous
.LBB0_414:
	s_mov_b64 s[0:1], 0
	s_waitcnt vmcnt(0)
	v_mov_b32_e32 v3, 0
	v_mov_b32_e32 v1, 0
	v_mov_b32_e32 v2, 0
	s_cmpk_gt_i32 s3, 0x3ff
	s_cbranch_scc1 .LBB0_423
	v_mul_f32_e32 v1, 0xc18293ee, v1
	v_mul_f32_e32 v142, v2, v1
	v_and_b32_e32 v2, 15, v0
	v_bfe_u32 v8, v0, 4, 6
	v_and_b32_e32 v1, 0x3ff, v0
	v_bfe_u32 v3, v0, 2, 2
	v_lshrrev_b32_e32 v6, 1, v0
	v_lshrrev_b32_e32 v7, 5, v0
	v_bitop3_b32 v2, v8, v2, 7 bitop3:0x6c
	v_and_b32_e32 v4, 0x60, v0
	v_lshlrev_b32_e32 v5, 3, v1
	v_and_b32_e32 v6, 8, v6
	v_and_or_b32 v3, v7, 4, v3
	v_lshlrev_b32_e32 v2, 4, v2
	v_and_or_b32 v4, v5, 24, v4
	v_or_b32_e32 v7, v3, v6
	v_lshl_or_b32 v146, v8, 8, v2
	v_and_b32_e32 v8, 16, v8
	v_lshlrev_b32_e32 v4, 1, v4
	v_or_b32_e32 v9, v7, v8
	s_add_u32 s9, s56, 0x12cb0000
	v_lshl_or_b32 v148, v9, 8, v4
	v_or_b32_e32 v9, 0x200, v1
	s_addc_u32 s20, s57, 0
	v_lshrrev_b32_e32 v9, 4, v9
	s_add_u32 s21, s56, 0x14eb0000
	v_lshl_or_b32 v150, v9, 8, v2
	v_and_b32_e32 v9, 48, v9
	s_addc_u32 s24, s57, 0
	v_or_b32_e32 v2, v7, v9
	v_bfe_u32 v7, v0, 5, 1
	v_lshlrev_b32_e32 v10, 4, v1
	v_lshlrev_b32_e32 v12, 1, v1
	s_add_u32 s25, s56, 0xecb0000
	v_and_b32_e32 v144, 31, v0
	v_and_b32_e32 v11, 0xc0, v10
	v_and_b32_e32 v13, 32, v12
	v_and_b32_e32 v5, 0x118, v5
	v_lshlrev_b32_e32 v182, 4, v7
	s_addc_u32 s28, s57, 0
	v_or3_b32 v5, v13, v11, v5
	v_lshlrev_b32_e32 v11, 8, v144
	v_and_b32_e32 v10, 0x70, v10
	v_or_b32_e32 v13, 32, v182
	s_add_u32 s29, s56, 0x13db0000
	v_bitop3_b32 v184, v13, v11, v10 bitop3:0xde
	v_or_b32_e32 v13, 64, v182
	s_addc_u32 s30, s57, 0
	v_bitop3_b32 v185, v13, v11, v10 bitop3:0xde
	v_or_b32_e32 v13, 0x60, v182
	s_cmp_lg_u32 0, -1
	v_bitop3_b32 v186, v13, v11, v10 bitop3:0xde
	v_or_b32_e32 v13, 0x80, v182
	v_lshl_or_b32 v152, v2, 8, v4
	v_and_b32_e32 v4, 63, v0
	s_cselect_b32 s0, 0, 0
	v_bitop3_b32 v187, v13, v11, v10 bitop3:0xde
	v_or_b32_e32 v13, 0xa0, v182
	v_lshlrev_b32_e32 v2, 3, v7
	v_add_u32_e32 v145, s0, v5
	v_bitop3_b32 v188, v13, v11, v10 bitop3:0xde
	v_or_b32_e32 v13, 0xc0, v182
	s_add_i32 s0, s0, 0x8000
	v_cmp_gt_u32_e32 vcc, 32, v4
	v_lshlrev_b32_e32 v156, 13, v7
	v_or3_b32 v4, v8, v6, v3
	v_lshlrev_b32_e32 v7, 4, v0
	v_or3_b32 v3, v9, v6, v3
	s_waitcnt lgkmcnt(0)
	v_mov_b32_e32 v155, 0
	v_bitop3_b32 v189, v13, v11, v10 bitop3:0xde
	v_or_b32_e32 v13, 0xe0, v182
	v_add_u32_e32 v191, s0, v5
	v_lshlrev_b32_e32 v4, 8, v4
	v_and_b32_e32 v5, 0xc0, v12
	v_and_b32_e32 v7, 48, v7
	v_lshlrev_b32_e32 v3, 8, v3
	v_mov_b32_e32 v149, v155
	v_mov_b32_e32 v147, v155
	v_mov_b32_e32 v153, v155
	v_mov_b32_e32 v151, v155
	s_mov_b32 s7, 0
	v_bitop3_b32 v183, v182, v11, v10 bitop3:0xde
	v_bitop3_b32 v190, v13, v11, v10 bitop3:0xde
	s_mov_b32 s31, 0x8000
	v_mov_b32_e32 v157, v155
	v_mov_b32_e32 v143, v142
	v_mov_b32_e32 v158, v142
	v_mov_b32_e32 v159, v142
	v_or3_b32 v160, v4, v5, v7
	v_mov_b32_e32 v161, v155
	v_or3_b32 v162, v3, v5, v7
	v_mov_b32_e32 v163, v155
	s_movk_i32 s38, 0x4000
	s_mov_b32 s39, 0xc000
	s_mov_b32 s8, 0x3e0293ee
	s_mov_b64 s[10:11], 0x13db8000
	s_mov_b64 s[12:13], 0x12cb8000
	s_mov_b64 s[14:15], 0x13dbc000
	s_mov_b64 s[16:17], 0x12cbc000
	v_lshlrev_b32_e32 v154, 1, v144
	s_movk_i32 s40, 0x1000
	s_movk_i32 s41, 0x5000
	s_mov_b32 s42, 0x9000
	s_mov_b32 s43, 0xd000
	v_lshlrev_b32_e32 v164, 1, v2
	s_branch .LBB0_419
.LBB0_418:
.LBB0_419:
	s_ashr_i32 s6, s3, 7
	s_lshl_b32 s1, s3, 8
	s_lshl_b32 s0, s6, 12
	s_and_b32 s1, s1, 0xf00
	s_bfe_u32 s18, s3, 0x10006
	s_or_b32 s0, s0, s1
	s_lshl_b32 s44, s3, 3
	s_ashr_i32 s1, s0, 31
	s_lshl_b32 s19, s18, 9
	s_and_b32 s44, s44, 0x180
	s_lshl_b64 s[0:1], s[0:1], 10
	s_or_b32 s19, s19, s44
	s_or_b32 s0, s0, s19
	s_lshl_b32 s6, s6, 1
	s_or_b32 s18, s6, s18
	s_lshl_b64 s[0:1], s[0:1], 1
	s_add_u32 s60, s25, s0
	s_addc_u32 s61, s28, s1
	s_add_u32 s46, s21, s0
	s_addc_u32 s47, s24, s1
	s_mul_hi_i32 s19, s18, 0x110000
	s_mul_i32 s18, s18, 0x110000
	s_add_u32 s62, s9, s18
	s_addc_u32 s63, s20, s19
	s_add_u32 s64, s29, s18
	s_addc_u32 s65, s30, s19
	v_readfirstlane_b32 s44, v1
	s_lshr_b32 s6, s44, 6
	s_lshl_b32 s45, s6, 10
	s_lshl_b32 s44, s6, 9
	s_add_i32 s44, s44, 0x20000
	v_and_b32_e32 v136, 15, v1
	v_bfe_u32 v137, v1, 4, 2
	v_lshrrev_b32_e32 v130, 4, v1
	v_xor_b32_e32 v131, v1, v130
	v_and_b32_e32 v131, 15, v131
	v_lshlrev_b32_e32 v131, 4, v131
	v_lshl_or_b32 v150, v130, 8, v131
	v_add_u32_e32 v151, 0x2000, v150
	v_and_b32_e32 v131, 7, v130
	v_lshlrev_b32_e32 v131, 1, v131
	v_xor_b32_e32 v131, v1, v131
	v_and_b32_e32 v131, 15, v131
	v_lshlrev_b32_e32 v131, 4, v131
	v_lshl_or_b32 v152, v130, 8, v131
	v_add_u32_e32 v153, 0x2000, v152
	v_lshlrev_b32_e32 v130, 8, v136
	v_add_u32_e32 v131, 0, v137
	v_xor_b32_e32 v131, v131, v136
	v_lshl_or_b32 v183, v131, 4, v130
	v_add_u32_e32 v187, 0x10000, v183
	v_add_u32_e32 v131, 4, v137
	v_xor_b32_e32 v131, v131, v136
	v_lshl_or_b32 v184, v131, 4, v130
	v_add_u32_e32 v188, 0x10000, v184
	v_add_u32_e32 v131, 8, v137
	v_xor_b32_e32 v131, v131, v136
	v_lshl_or_b32 v185, v131, 4, v130
	v_add_u32_e32 v189, 0x10000, v185
	v_add_u32_e32 v131, 12, v137
	v_xor_b32_e32 v131, v131, v136
	v_lshl_or_b32 v186, v131, 4, v130
	v_add_u32_e32 v190, 0x10000, v186
	v_bfe_u32 v130, v1, 2, 2
	v_lshl_or_b32 v131, v137, 2, v130
	v_and_b32_e32 v132, 7, v131
	v_and_b32_e32 v133, 3, v1
	v_lshlrev_b32_e32 v133, 3, v133
	v_lshl_or_b32 v133, v131, 8, v133
	v_xor_b32_e32 v134, 0, v132
	v_lshl_or_b32 v240, v134, 5, v133
	v_add_u32_e32 v142, 0x10000, v240
	v_xor_b32_e32 v134, 1, v132
	v_lshl_or_b32 v241, v134, 5, v133
	v_add_u32_e32 v143, 0x10000, v241
	v_xor_b32_e32 v134, 2, v132
	v_lshl_or_b32 v242, v134, 5, v133
	v_add_u32_e32 v144, 0x10000, v242
	v_xor_b32_e32 v134, 3, v132
	v_lshl_or_b32 v243, v134, 5, v133
	v_add_u32_e32 v145, 0x10000, v243
	v_xor_b32_e32 v134, 4, v132
	v_lshl_or_b32 v244, v134, 5, v133
	v_add_u32_e32 v146, 0x10000, v244
	v_xor_b32_e32 v134, 5, v132
	v_lshl_or_b32 v245, v134, 5, v133
	v_add_u32_e32 v147, 0x10000, v245
	v_xor_b32_e32 v134, 6, v132
	v_lshl_or_b32 v246, v134, 5, v133
	v_add_u32_e32 v148, 0x10000, v246
	v_xor_b32_e32 v134, 7, v132
	v_lshl_or_b32 v247, v134, 5, v133
	v_add_u32_e32 v149, 0x10000, v247
	s_lshl_b32 s18, s6, 16
	v_lshlrev_b32_e32 v130, 11, v136
	v_lshl_or_b32 v130, v137, 4, v130
	v_add_u32_e32 v154, s18, v130
	v_add_u32_e32 v155, 0x8000, v154
	v_lshlrev_b32_e32 v130, 13, v137
	v_lshl_or_b32 v130, v136, 1, v130
	v_add_u32_e32 v156, s18, v130
	v_add_u32_e32 v157, 0x1000, v156
	v_add_u32_e32 v158, 0x8000, v156
	v_add_u32_e32 v159, 0x9000, v156
	v_and_b32_e32 v130, 63, v1
	v_lshl_add_u32 v160, v130, 2, s44
	v_lshl_add_u32 v161, v137, 4, s44
	s_add_i32 m0, s45, 0x0
	s_nop 0
	global_load_lds_dwordx4 v152, s[64:65]
	s_add_i32 m0, s45, 0x4000
	s_nop 0
	global_load_lds_dwordx4 v150, s[62:63]
	s_add_i32 m0, s45, 0x2000
	s_nop 0
	global_load_lds_dwordx4 v153, s[64:65]
	s_add_i32 m0, s45, 0x6000
	s_nop 0
	global_load_lds_dwordx4 v151, s[62:63]
	s_add_u32 s62, s62, 0x4000
	s_addc_u32 s63, s63, 0
	s_add_u32 s64, s64, 0x4000
	s_addc_u32 s65, s65, 0
	s_add_i32 m0, s45, 0x8000
	s_nop 0
	global_load_lds_dwordx4 v152, s[64:65]
	s_add_i32 m0, s45, 0xc000
	s_nop 0
	global_load_lds_dwordx4 v150, s[62:63]
	s_add_i32 m0, s45, 0xa000
	s_nop 0
	global_load_lds_dwordx4 v153, s[64:65]
	s_add_i32 m0, s45, 0xe000
	s_nop 0
	global_load_lds_dwordx4 v151, s[62:63]
	s_add_u32 s62, s62, 0x4000
	s_addc_u32 s63, s63, 0
	s_add_u32 s64, s64, 0x4000
	s_addc_u32 s65, s65, 0
	global_load_dwordx4 v[98:101], v154, s[60:61]
	global_load_dwordx4 v[102:105], v154, s[60:61] offset:64
	global_load_dwordx4 v[106:109], v154, s[60:61] offset:128
	global_load_dwordx4 v[110:113], v154, s[60:61] offset:192
	global_load_dwordx4 v[114:117], v155, s[60:61]
	global_load_dwordx4 v[118:121], v155, s[60:61] offset:64
	global_load_dwordx4 v[122:125], v155, s[60:61] offset:128
	global_load_dwordx4 v[126:129], v155, s[60:61] offset:192
	v_mov_b32_e32 v2, 0
	v_mov_b32_e32 v3, 0
	v_mov_b32_e32 v4, 0
	v_mov_b32_e32 v5, 0
	v_mov_b32_e32 v6, 0
	v_mov_b32_e32 v7, 0
	v_mov_b32_e32 v8, 0
	v_mov_b32_e32 v9, 0
	v_mov_b32_e32 v10, 0
	v_mov_b32_e32 v11, 0
	v_mov_b32_e32 v12, 0
	v_mov_b32_e32 v13, 0
	v_mov_b32_e32 v14, 0
	v_mov_b32_e32 v15, 0
	v_mov_b32_e32 v16, 0
	v_mov_b32_e32 v17, 0
	v_mov_b32_e32 v18, 0
	v_mov_b32_e32 v19, 0
	v_mov_b32_e32 v20, 0
	v_mov_b32_e32 v21, 0
	v_mov_b32_e32 v22, 0
	v_mov_b32_e32 v23, 0
	v_mov_b32_e32 v24, 0
	v_mov_b32_e32 v25, 0
	v_mov_b32_e32 v26, 0
	v_mov_b32_e32 v27, 0
	v_mov_b32_e32 v28, 0
	v_mov_b32_e32 v29, 0
	v_mov_b32_e32 v30, 0
	v_mov_b32_e32 v31, 0
	v_mov_b32_e32 v32, 0
	v_mov_b32_e32 v33, 0
	v_mov_b32_e32 v34, 0
	v_mov_b32_e32 v35, 0
	v_mov_b32_e32 v36, 0
	v_mov_b32_e32 v37, 0
	v_mov_b32_e32 v38, 0
	v_mov_b32_e32 v39, 0
	v_mov_b32_e32 v40, 0
	v_mov_b32_e32 v41, 0
	v_mov_b32_e32 v42, 0
	v_mov_b32_e32 v43, 0
	v_mov_b32_e32 v44, 0
	v_mov_b32_e32 v45, 0
	v_mov_b32_e32 v46, 0
	v_mov_b32_e32 v47, 0
	v_mov_b32_e32 v48, 0
	v_mov_b32_e32 v49, 0
	v_mov_b32_e32 v50, 0
	v_mov_b32_e32 v51, 0
	v_mov_b32_e32 v52, 0
	v_mov_b32_e32 v53, 0
	v_mov_b32_e32 v54, 0
	v_mov_b32_e32 v55, 0
	v_mov_b32_e32 v56, 0
	v_mov_b32_e32 v57, 0
	v_mov_b32_e32 v58, 0
	v_mov_b32_e32 v59, 0
	v_mov_b32_e32 v60, 0
	v_mov_b32_e32 v61, 0
	v_mov_b32_e32 v62, 0
	v_mov_b32_e32 v63, 0
	v_mov_b32_e32 v64, 0
	v_mov_b32_e32 v65, 0
	v_mov_b32_e32 v165, 0
	v_mov_b32_e32 v163, 0
	s_waitcnt vmcnt(0)
	s_barrier
	ds_read_b128 v[166:169], v183 offset:16384
	ds_read_b128 v[170:173], v183 offset:20480
	ds_read_b128 v[174:177], v183 offset:24576
	ds_read_b128 v[178:181], v183 offset:28672
	ds_read_b128 v[224:227], v184 offset:16384
	ds_read_b128 v[228:231], v184 offset:20480
	ds_read_b128 v[232:235], v184 offset:24576
	ds_read_b128 v[236:239], v184 offset:28672
	s_waitcnt lgkmcnt(7)
	v_mfma_f32_16x16x32_bf16 v[66:69], v[166:169], v[98:101], 0
	v_mfma_f32_16x16x32_bf16 v[82:85], v[166:169], v[114:117], 0
	ds_read_b128 v[166:169], v185 offset:16384
	s_add_i32 m0, s45, 0x10000
	s_nop 0
	global_load_lds_dwordx4 v152, s[64:65]
	s_waitcnt lgkmcnt(7)
	v_mfma_f32_16x16x32_bf16 v[70:73], v[170:173], v[98:101], 0
	v_mfma_f32_16x16x32_bf16 v[86:89], v[170:173], v[114:117], 0
	ds_read_b128 v[170:173], v185 offset:20480
	s_add_i32 m0, s45, 0x14000
	s_nop 0
	global_load_lds_dwordx4 v150, s[62:63]
	s_waitcnt lgkmcnt(7)
	v_mfma_f32_16x16x32_bf16 v[74:77], v[174:177], v[98:101], 0
	v_mfma_f32_16x16x32_bf16 v[90:93], v[174:177], v[114:117], 0
	ds_read_b128 v[174:177], v185 offset:24576
	s_add_i32 m0, s45, 0x12000
	s_nop 0
	global_load_lds_dwordx4 v153, s[64:65]
	s_waitcnt lgkmcnt(7)
	v_mfma_f32_16x16x32_bf16 v[78:81], v[178:181], v[98:101], 0
	v_mfma_f32_16x16x32_bf16 v[94:97], v[178:181], v[114:117], 0
	ds_read_b128 v[178:181], v185 offset:28672
	s_add_i32 m0, s45, 0x16000
	s_nop 0
	global_load_lds_dwordx4 v151, s[62:63]
	s_add_u32 s62, s62, 0x4000
	s_addc_u32 s63, s63, 0
	s_add_u32 s64, s64, 0x4000
	s_addc_u32 s65, s65, 0
	s_waitcnt lgkmcnt(7)
	v_mfma_f32_16x16x32_bf16 v[66:69], v[224:227], v[102:105], v[66:69]
	v_mfma_f32_16x16x32_bf16 v[82:85], v[224:227], v[118:121], v[82:85]
	ds_read_b128 v[224:227], v186 offset:16384
	s_waitcnt lgkmcnt(7)
	v_mfma_f32_16x16x32_bf16 v[70:73], v[228:231], v[102:105], v[70:73]
	v_mfma_f32_16x16x32_bf16 v[86:89], v[228:231], v[118:121], v[86:89]
	ds_read_b128 v[228:231], v186 offset:20480
	s_waitcnt lgkmcnt(7)
	v_mfma_f32_16x16x32_bf16 v[74:77], v[232:235], v[102:105], v[74:77]
	v_mfma_f32_16x16x32_bf16 v[90:93], v[232:235], v[118:121], v[90:93]
	ds_read_b128 v[232:235], v186 offset:24576
	s_waitcnt lgkmcnt(7)
	v_mfma_f32_16x16x32_bf16 v[78:81], v[236:239], v[102:105], v[78:81]
	v_mfma_f32_16x16x32_bf16 v[94:97], v[236:239], v[118:121], v[94:97]
	ds_read_b128 v[236:239], v186 offset:28672
	s_waitcnt lgkmcnt(7)
	v_mfma_f32_16x16x32_bf16 v[66:69], v[166:169], v[106:109], v[66:69]
	v_mfma_f32_16x16x32_bf16 v[82:85], v[166:169], v[122:125], v[82:85]
	s_waitcnt lgkmcnt(6)
	v_mfma_f32_16x16x32_bf16 v[70:73], v[170:173], v[106:109], v[70:73]
	v_mfma_f32_16x16x32_bf16 v[86:89], v[170:173], v[122:125], v[86:89]
	s_waitcnt lgkmcnt(5)
	v_mfma_f32_16x16x32_bf16 v[74:77], v[174:177], v[106:109], v[74:77]
	v_mfma_f32_16x16x32_bf16 v[90:93], v[174:177], v[122:125], v[90:93]
	s_waitcnt lgkmcnt(4)
	v_mfma_f32_16x16x32_bf16 v[78:81], v[178:181], v[106:109], v[78:81]
	v_mfma_f32_16x16x32_bf16 v[94:97], v[178:181], v[122:125], v[94:97]
	s_waitcnt lgkmcnt(3)
	v_mfma_f32_16x16x32_bf16 v[66:69], v[224:227], v[110:113], v[66:69]
	v_mfma_f32_16x16x32_bf16 v[82:85], v[224:227], v[126:129], v[82:85]
	s_waitcnt lgkmcnt(2)
	v_mfma_f32_16x16x32_bf16 v[70:73], v[228:231], v[110:113], v[70:73]
	v_mfma_f32_16x16x32_bf16 v[86:89], v[228:231], v[126:129], v[86:89]
	s_waitcnt lgkmcnt(1)
	v_mfma_f32_16x16x32_bf16 v[74:77], v[232:235], v[110:113], v[74:77]
	v_mfma_f32_16x16x32_bf16 v[90:93], v[232:235], v[126:129], v[90:93]
	s_waitcnt lgkmcnt(0)
	v_mfma_f32_16x16x32_bf16 v[78:81], v[236:239], v[110:113], v[78:81]
	v_mfma_f32_16x16x32_bf16 v[94:97], v[236:239], v[126:129], v[94:97]
	s_nop 7
	s_nop 3
	v_exp_f32_e32 v66, v66
	v_exp_f32_e32 v67, v67
	v_exp_f32_e32 v68, v68
	v_exp_f32_e32 v69, v69
	v_exp_f32_e32 v82, v82
	v_exp_f32_e32 v83, v83
	v_exp_f32_e32 v84, v84
	v_exp_f32_e32 v85, v85
	v_exp_f32_e32 v70, v70
	v_exp_f32_e32 v71, v71
	v_exp_f32_e32 v72, v72
	v_exp_f32_e32 v73, v73
	v_exp_f32_e32 v86, v86
	v_exp_f32_e32 v87, v87
	v_exp_f32_e32 v88, v88
	v_exp_f32_e32 v89, v89
	v_exp_f32_e32 v74, v74
	v_exp_f32_e32 v75, v75
	v_exp_f32_e32 v76, v76
	v_exp_f32_e32 v77, v77
	v_exp_f32_e32 v90, v90
	v_exp_f32_e32 v91, v91
	v_exp_f32_e32 v92, v92
	v_exp_f32_e32 v93, v93
	v_exp_f32_e32 v78, v78
	v_exp_f32_e32 v79, v79
	v_exp_f32_e32 v80, v80
	v_exp_f32_e32 v81, v81
	v_exp_f32_e32 v94, v94
	v_exp_f32_e32 v95, v95
	v_exp_f32_e32 v96, v96
	v_exp_f32_e32 v97, v97
	ds_read_b128 v[166:169], v183 offset:49152
	ds_read_b128 v[170:173], v183 offset:53248
	ds_read_b128 v[174:177], v183 offset:57344
	ds_read_b128 v[178:181], v183 offset:61440
	ds_read_b128 v[224:227], v184 offset:49152
	ds_read_b128 v[228:231], v184 offset:53248
	ds_read_b128 v[232:235], v184 offset:57344
	ds_read_b128 v[236:239], v184 offset:61440
	s_waitcnt vmcnt(0)
	s_barrier
	s_mov_b32 s66, 16
.Lattn_loop:
	s_waitcnt lgkmcnt(7)
	v_mfma_f32_16x16x32_bf16 v[192:195], v[166:169], v[98:101], 0
	v_mfma_f32_16x16x32_bf16 v[208:211], v[166:169], v[114:117], 0
	ds_read_b128 v[166:169], v185 offset:49152
	s_add_i32 m0, s45, 0x18000
	v_add_f32_e32 v130, v66, v67
	v_add_f32_e32 v131, v68, v69
	v_add_f32_e32 v130, v70, v130
	global_load_lds_dwordx4 v152, s[64:65]
	s_waitcnt lgkmcnt(7)
	v_mfma_f32_16x16x32_bf16 v[196:199], v[170:173], v[98:101], 0
	v_mfma_f32_16x16x32_bf16 v[212:215], v[170:173], v[114:117], 0
	ds_read_b128 v[170:173], v185 offset:53248
	s_add_i32 m0, s45, 0x1c000
	v_add_f32_e32 v131, v71, v131
	v_add_f32_e32 v130, v72, v130
	v_add_f32_e32 v131, v73, v131
	global_load_lds_dwordx4 v150, s[62:63]
	s_waitcnt lgkmcnt(7)
	v_mfma_f32_16x16x32_bf16 v[200:203], v[174:177], v[98:101], 0
	v_mfma_f32_16x16x32_bf16 v[216:219], v[174:177], v[114:117], 0
	ds_read_b128 v[174:177], v185 offset:57344
	s_add_i32 m0, s45, 0x1a000
	v_add_f32_e32 v130, v74, v130
	v_add_f32_e32 v131, v75, v131
	v_add_f32_e32 v130, v76, v130
	global_load_lds_dwordx4 v153, s[64:65]
	s_waitcnt lgkmcnt(7)
	v_mfma_f32_16x16x32_bf16 v[204:207], v[178:181], v[98:101], 0
	v_mfma_f32_16x16x32_bf16 v[220:223], v[178:181], v[114:117], 0
	ds_read_b128 v[178:181], v185 offset:61440
	s_add_i32 m0, s45, 0x1e000
	v_add_f32_e32 v131, v77, v131
	v_add_f32_e32 v130, v78, v130
	v_add_f32_e32 v131, v79, v131
	global_load_lds_dwordx4 v151, s[62:63]
	s_add_u32 s62, s62, 0x4000
	s_addc_u32 s63, s63, 0
	s_add_u32 s64, s64, 0x4000
	s_addc_u32 s65, s65, 0
	s_waitcnt lgkmcnt(7)
	v_mfma_f32_16x16x32_bf16 v[192:195], v[224:227], v[102:105], v[192:195]
	v_mfma_f32_16x16x32_bf16 v[208:211], v[224:227], v[118:121], v[208:211]
	ds_read_b128 v[224:227], v186 offset:49152
	v_add_f32_e32 v130, v80, v130
	v_add_f32_e32 v131, v81, v131
	v_add_f32_e32 v130, v130, v131
	s_waitcnt lgkmcnt(7)
	v_mfma_f32_16x16x32_bf16 v[196:199], v[228:231], v[102:105], v[196:199]
	v_mfma_f32_16x16x32_bf16 v[212:215], v[228:231], v[118:121], v[212:215]
	ds_read_b128 v[228:231], v186 offset:53248
	v_add_f32_e32 v165, v165, v130
	v_add_f32_e32 v132, v82, v83
	v_add_f32_e32 v133, v84, v85
	s_waitcnt lgkmcnt(7)
	v_mfma_f32_16x16x32_bf16 v[200:203], v[232:235], v[102:105], v[200:203]
	v_mfma_f32_16x16x32_bf16 v[216:219], v[232:235], v[118:121], v[216:219]
	ds_read_b128 v[232:235], v186 offset:57344
	v_add_f32_e32 v132, v86, v132
	v_add_f32_e32 v133, v87, v133
	v_add_f32_e32 v132, v88, v132
	s_waitcnt lgkmcnt(7)
	v_mfma_f32_16x16x32_bf16 v[204:207], v[236:239], v[102:105], v[204:207]
	v_mfma_f32_16x16x32_bf16 v[220:223], v[236:239], v[118:121], v[220:223]
	ds_read_b128 v[236:239], v186 offset:61440
	v_add_f32_e32 v133, v89, v133
	v_add_f32_e32 v132, v90, v132
	v_add_f32_e32 v133, v91, v133
	s_waitcnt lgkmcnt(7)
	v_mfma_f32_16x16x32_bf16 v[192:195], v[166:169], v[106:109], v[192:195]
	v_mfma_f32_16x16x32_bf16 v[208:211], v[166:169], v[122:125], v[208:211]
	ds_read_b64_tr_b16 v[166:167], v240 offset:0
	ds_read_b64_tr_b16 v[168:169], v240 offset:4096
	v_add_f32_e32 v132, v92, v132
	v_add_f32_e32 v133, v93, v133
	v_add_f32_e32 v132, v94, v132
	s_waitcnt lgkmcnt(8)
	v_mfma_f32_16x16x32_bf16 v[196:199], v[170:173], v[106:109], v[196:199]
	v_mfma_f32_16x16x32_bf16 v[212:215], v[170:173], v[122:125], v[212:215]
	ds_read_b64_tr_b16 v[170:171], v241 offset:0
	ds_read_b64_tr_b16 v[172:173], v241 offset:4096
	v_add_f32_e32 v133, v95, v133
	v_add_f32_e32 v132, v96, v132
	v_add_f32_e32 v133, v97, v133
	s_waitcnt lgkmcnt(9)
	v_mfma_f32_16x16x32_bf16 v[200:203], v[174:177], v[106:109], v[200:203]
	v_mfma_f32_16x16x32_bf16 v[216:219], v[174:177], v[122:125], v[216:219]
	ds_read_b64_tr_b16 v[174:175], v242 offset:0
	ds_read_b64_tr_b16 v[176:177], v242 offset:4096
	v_add_f32_e32 v132, v132, v133
	v_add_f32_e32 v163, v163, v132
	v_cvt_pk_bf16_f32 v66, v66, v67
	s_waitcnt lgkmcnt(10)
	v_mfma_f32_16x16x32_bf16 v[204:207], v[178:181], v[106:109], v[204:207]
	v_mfma_f32_16x16x32_bf16 v[220:223], v[178:181], v[122:125], v[220:223]
	ds_read_b64_tr_b16 v[178:179], v243 offset:0
	ds_read_b64_tr_b16 v[180:181], v243 offset:4096
	v_cvt_pk_bf16_f32 v67, v68, v69
	v_cvt_pk_bf16_f32 v68, v70, v71
	v_cvt_pk_bf16_f32 v69, v72, v73
	s_waitcnt lgkmcnt(11)
	v_mfma_f32_16x16x32_bf16 v[192:195], v[224:227], v[110:113], v[192:195]
	v_mfma_f32_16x16x32_bf16 v[208:211], v[224:227], v[126:129], v[208:211]
	ds_read_b64_tr_b16 v[224:225], v244 offset:0
	ds_read_b64_tr_b16 v[226:227], v244 offset:4096
	v_cvt_pk_bf16_f32 v74, v74, v75
	v_cvt_pk_bf16_f32 v75, v76, v77
	v_cvt_pk_bf16_f32 v76, v78, v79
	s_waitcnt lgkmcnt(12)
	v_mfma_f32_16x16x32_bf16 v[196:199], v[228:231], v[110:113], v[196:199]
	v_mfma_f32_16x16x32_bf16 v[212:215], v[228:231], v[126:129], v[212:215]
	ds_read_b64_tr_b16 v[228:229], v245 offset:0
	ds_read_b64_tr_b16 v[230:231], v245 offset:4096
	v_cvt_pk_bf16_f32 v77, v80, v81
	v_cvt_pk_bf16_f32 v82, v82, v83
	v_cvt_pk_bf16_f32 v83, v84, v85
	s_waitcnt lgkmcnt(13)
	v_mfma_f32_16x16x32_bf16 v[200:203], v[232:235], v[110:113], v[200:203]
	v_mfma_f32_16x16x32_bf16 v[216:219], v[232:235], v[126:129], v[216:219]
	v_cvt_pk_bf16_f32 v84, v86, v87
	v_cvt_pk_bf16_f32 v85, v88, v89
	v_cvt_pk_bf16_f32 v90, v90, v91
	s_waitcnt lgkmcnt(12)
	v_mfma_f32_16x16x32_bf16 v[204:207], v[236:239], v[110:113], v[204:207]
	v_mfma_f32_16x16x32_bf16 v[220:223], v[236:239], v[126:129], v[220:223]
	v_cvt_pk_bf16_f32 v91, v92, v93
	v_cvt_pk_bf16_f32 v92, v94, v95
	v_cvt_pk_bf16_f32 v93, v96, v97
	s_waitcnt lgkmcnt(10)
	v_mfma_f32_16x16x32_bf16 v[2:5], v[66:69], v[166:169], v[2:5]
	v_mfma_f32_16x16x32_bf16 v[34:37], v[82:85], v[166:169], v[34:37]
	ds_read_b64_tr_b16 v[232:233], v246 offset:0
	ds_read_b64_tr_b16 v[234:235], v246 offset:4096
	s_waitcnt lgkmcnt(10)
	v_mfma_f32_16x16x32_bf16 v[6:9], v[66:69], v[170:173], v[6:9]
	v_mfma_f32_16x16x32_bf16 v[38:41], v[82:85], v[170:173], v[38:41]
	ds_read_b64_tr_b16 v[236:237], v247 offset:0
	ds_read_b64_tr_b16 v[238:239], v247 offset:4096
	s_waitcnt lgkmcnt(10)
	v_mfma_f32_16x16x32_bf16 v[10:13], v[66:69], v[174:177], v[10:13]
	v_mfma_f32_16x16x32_bf16 v[42:45], v[82:85], v[174:177], v[42:45]
	ds_read_b64_tr_b16 v[166:167], v240 offset:8192
	ds_read_b64_tr_b16 v[168:169], v240 offset:12288
	v_exp_f32_e32 v192, v192
	v_exp_f32_e32 v193, v193
	v_exp_f32_e32 v194, v194
	s_waitcnt lgkmcnt(10)
	v_mfma_f32_16x16x32_bf16 v[14:17], v[66:69], v[178:181], v[14:17]
	v_mfma_f32_16x16x32_bf16 v[46:49], v[82:85], v[178:181], v[46:49]
	ds_read_b64_tr_b16 v[170:171], v241 offset:8192
	ds_read_b64_tr_b16 v[172:173], v241 offset:12288
	v_exp_f32_e32 v195, v195
	v_exp_f32_e32 v208, v208
	s_waitcnt lgkmcnt(10)
	v_mfma_f32_16x16x32_bf16 v[18:21], v[66:69], v[224:227], v[18:21]
	v_mfma_f32_16x16x32_bf16 v[50:53], v[82:85], v[224:227], v[50:53]
	ds_read_b64_tr_b16 v[174:175], v242 offset:8192
	ds_read_b64_tr_b16 v[176:177], v242 offset:12288
	v_exp_f32_e32 v209, v209
	v_exp_f32_e32 v210, v210
	s_waitcnt lgkmcnt(10)
	v_mfma_f32_16x16x32_bf16 v[22:25], v[66:69], v[228:231], v[22:25]
	v_mfma_f32_16x16x32_bf16 v[54:57], v[82:85], v[228:231], v[54:57]
	ds_read_b64_tr_b16 v[178:179], v243 offset:8192
	ds_read_b64_tr_b16 v[180:181], v243 offset:12288
	v_exp_f32_e32 v211, v211
	v_exp_f32_e32 v196, v196
	v_exp_f32_e32 v197, v197
	s_waitcnt lgkmcnt(10)
	v_mfma_f32_16x16x32_bf16 v[26:29], v[66:69], v[232:235], v[26:29]
	v_mfma_f32_16x16x32_bf16 v[58:61], v[82:85], v[232:235], v[58:61]
	ds_read_b64_tr_b16 v[224:225], v244 offset:8192
	ds_read_b64_tr_b16 v[226:227], v244 offset:12288
	v_exp_f32_e32 v198, v198
	v_exp_f32_e32 v199, v199
	s_waitcnt lgkmcnt(10)
	v_mfma_f32_16x16x32_bf16 v[30:33], v[66:69], v[236:239], v[30:33]
	v_mfma_f32_16x16x32_bf16 v[62:65], v[82:85], v[236:239], v[62:65]
	ds_read_b64_tr_b16 v[228:229], v245 offset:8192
	ds_read_b64_tr_b16 v[230:231], v245 offset:12288
	v_exp_f32_e32 v212, v212
	v_exp_f32_e32 v213, v213
	s_waitcnt lgkmcnt(10)
	v_mfma_f32_16x16x32_bf16 v[2:5], v[74:77], v[166:169], v[2:5]
	v_mfma_f32_16x16x32_bf16 v[34:37], v[90:93], v[166:169], v[34:37]
	ds_read_b64_tr_b16 v[232:233], v246 offset:8192
	ds_read_b64_tr_b16 v[234:235], v246 offset:12288
	ds_read_b128 v[166:169], v187 offset:16384
	v_exp_f32_e32 v214, v214
	v_exp_f32_e32 v215, v215
	s_waitcnt lgkmcnt(11)
	v_mfma_f32_16x16x32_bf16 v[6:9], v[74:77], v[170:173], v[6:9]
	v_mfma_f32_16x16x32_bf16 v[38:41], v[90:93], v[170:173], v[38:41]
	ds_read_b64_tr_b16 v[236:237], v247 offset:8192
	ds_read_b64_tr_b16 v[238:239], v247 offset:12288
	ds_read_b128 v[170:173], v187 offset:20480
	v_exp_f32_e32 v200, v200
	v_exp_f32_e32 v201, v201
	v_exp_f32_e32 v202, v202
	s_waitcnt lgkmcnt(12)
	v_mfma_f32_16x16x32_bf16 v[10:13], v[74:77], v[174:177], v[10:13]
	v_mfma_f32_16x16x32_bf16 v[42:45], v[90:93], v[174:177], v[42:45]
	ds_read_b128 v[174:177], v187 offset:24576
	v_exp_f32_e32 v203, v203
	v_exp_f32_e32 v216, v216
	s_waitcnt lgkmcnt(11)
	v_mfma_f32_16x16x32_bf16 v[14:17], v[74:77], v[178:181], v[14:17]
	v_mfma_f32_16x16x32_bf16 v[46:49], v[90:93], v[178:181], v[46:49]
	ds_read_b128 v[178:181], v187 offset:28672
	v_exp_f32_e32 v217, v217
	v_exp_f32_e32 v218, v218
	s_waitcnt lgkmcnt(10)
	v_mfma_f32_16x16x32_bf16 v[18:21], v[74:77], v[224:227], v[18:21]
	v_mfma_f32_16x16x32_bf16 v[50:53], v[90:93], v[224:227], v[50:53]
	ds_read_b128 v[224:227], v188 offset:16384
	v_exp_f32_e32 v219, v219
	v_exp_f32_e32 v204, v204
	v_exp_f32_e32 v205, v205
	s_waitcnt lgkmcnt(9)
	v_mfma_f32_16x16x32_bf16 v[22:25], v[74:77], v[228:231], v[22:25]
	v_mfma_f32_16x16x32_bf16 v[54:57], v[90:93], v[228:231], v[54:57]
	ds_read_b128 v[228:231], v188 offset:20480
	v_exp_f32_e32 v206, v206
	v_exp_f32_e32 v207, v207
	s_waitcnt lgkmcnt(8)
	v_mfma_f32_16x16x32_bf16 v[26:29], v[74:77], v[232:235], v[26:29]
	v_mfma_f32_16x16x32_bf16 v[58:61], v[90:93], v[232:235], v[58:61]
	ds_read_b128 v[232:235], v188 offset:24576
	v_exp_f32_e32 v220, v220
	v_exp_f32_e32 v221, v221
	s_waitcnt lgkmcnt(6)
	v_mfma_f32_16x16x32_bf16 v[30:33], v[74:77], v[236:239], v[30:33]
	v_mfma_f32_16x16x32_bf16 v[62:65], v[90:93], v[236:239], v[62:65]
	ds_read_b128 v[236:239], v188 offset:28672
	v_exp_f32_e32 v222, v222
	v_exp_f32_e32 v223, v223
	s_waitcnt vmcnt(0)
	s_barrier
	v_mfma_f32_16x16x32_bf16 v[66:69], v[166:169], v[98:101], 0
	v_mfma_f32_16x16x32_bf16 v[82:85], v[166:169], v[114:117], 0
	ds_read_b128 v[166:169], v189 offset:16384
	s_add_i32 m0, s45, 0x0
	v_add_f32_e32 v130, v192, v193
	v_add_f32_e32 v131, v194, v195
	v_add_f32_e32 v130, v196, v130
	global_load_lds_dwordx4 v152, s[64:65]
	s_waitcnt lgkmcnt(7)
	v_mfma_f32_16x16x32_bf16 v[70:73], v[170:173], v[98:101], 0
	v_mfma_f32_16x16x32_bf16 v[86:89], v[170:173], v[114:117], 0
	ds_read_b128 v[170:173], v189 offset:20480
	s_add_i32 m0, s45, 0x4000
	v_add_f32_e32 v131, v197, v131
	v_add_f32_e32 v130, v198, v130
	v_add_f32_e32 v131, v199, v131
	global_load_lds_dwordx4 v150, s[62:63]
	s_waitcnt lgkmcnt(7)
	v_mfma_f32_16x16x32_bf16 v[74:77], v[174:177], v[98:101], 0
	v_mfma_f32_16x16x32_bf16 v[90:93], v[174:177], v[114:117], 0
	ds_read_b128 v[174:177], v189 offset:24576
	s_add_i32 m0, s45, 0x2000
	v_add_f32_e32 v130, v200, v130
	v_add_f32_e32 v131, v201, v131
	v_add_f32_e32 v130, v202, v130
	global_load_lds_dwordx4 v153, s[64:65]
	s_waitcnt lgkmcnt(7)
	v_mfma_f32_16x16x32_bf16 v[78:81], v[178:181], v[98:101], 0
	v_mfma_f32_16x16x32_bf16 v[94:97], v[178:181], v[114:117], 0
	ds_read_b128 v[178:181], v189 offset:28672
	s_add_i32 m0, s45, 0x6000
	v_add_f32_e32 v131, v203, v131
	v_add_f32_e32 v130, v204, v130
	v_add_f32_e32 v131, v205, v131
	global_load_lds_dwordx4 v151, s[62:63]
	s_add_u32 s62, s62, 0x4000
	s_addc_u32 s63, s63, 0
	s_add_u32 s64, s64, 0x4000
	s_addc_u32 s65, s65, 0
	s_waitcnt lgkmcnt(7)
	v_mfma_f32_16x16x32_bf16 v[66:69], v[224:227], v[102:105], v[66:69]
	v_mfma_f32_16x16x32_bf16 v[82:85], v[224:227], v[118:121], v[82:85]
	ds_read_b128 v[224:227], v190 offset:16384
	v_add_f32_e32 v130, v206, v130
	v_add_f32_e32 v131, v207, v131
	v_add_f32_e32 v130, v130, v131
	s_waitcnt lgkmcnt(7)
	v_mfma_f32_16x16x32_bf16 v[70:73], v[228:231], v[102:105], v[70:73]
	v_mfma_f32_16x16x32_bf16 v[86:89], v[228:231], v[118:121], v[86:89]
	ds_read_b128 v[228:231], v190 offset:20480
	v_add_f32_e32 v165, v165, v130
	v_add_f32_e32 v132, v208, v209
	v_add_f32_e32 v133, v210, v211
	s_waitcnt lgkmcnt(7)
	v_mfma_f32_16x16x32_bf16 v[74:77], v[232:235], v[102:105], v[74:77]
	v_mfma_f32_16x16x32_bf16 v[90:93], v[232:235], v[118:121], v[90:93]
	ds_read_b128 v[232:235], v190 offset:24576
	v_add_f32_e32 v132, v212, v132
	v_add_f32_e32 v133, v213, v133
	v_add_f32_e32 v132, v214, v132
	s_waitcnt lgkmcnt(7)
	v_mfma_f32_16x16x32_bf16 v[78:81], v[236:239], v[102:105], v[78:81]
	v_mfma_f32_16x16x32_bf16 v[94:97], v[236:239], v[118:121], v[94:97]
	ds_read_b128 v[236:239], v190 offset:28672
	v_add_f32_e32 v133, v215, v133
	v_add_f32_e32 v132, v216, v132
	v_add_f32_e32 v133, v217, v133
	s_waitcnt lgkmcnt(7)
	v_mfma_f32_16x16x32_bf16 v[66:69], v[166:169], v[106:109], v[66:69]
	v_mfma_f32_16x16x32_bf16 v[82:85], v[166:169], v[122:125], v[82:85]
	ds_read_b64_tr_b16 v[166:167], v240 offset:32768
	ds_read_b64_tr_b16 v[168:169], v240 offset:36864
	v_add_f32_e32 v132, v218, v132
	v_add_f32_e32 v133, v219, v133
	v_add_f32_e32 v132, v220, v132
	s_waitcnt lgkmcnt(8)
	v_mfma_f32_16x16x32_bf16 v[70:73], v[170:173], v[106:109], v[70:73]
	v_mfma_f32_16x16x32_bf16 v[86:89], v[170:173], v[122:125], v[86:89]
	ds_read_b64_tr_b16 v[170:171], v241 offset:32768
	ds_read_b64_tr_b16 v[172:173], v241 offset:36864
	v_add_f32_e32 v133, v221, v133
	v_add_f32_e32 v132, v222, v132
	v_add_f32_e32 v133, v223, v133
	s_waitcnt lgkmcnt(9)
	v_mfma_f32_16x16x32_bf16 v[74:77], v[174:177], v[106:109], v[74:77]
	v_mfma_f32_16x16x32_bf16 v[90:93], v[174:177], v[122:125], v[90:93]
	ds_read_b64_tr_b16 v[174:175], v242 offset:32768
	ds_read_b64_tr_b16 v[176:177], v242 offset:36864
	v_add_f32_e32 v132, v132, v133
	v_add_f32_e32 v163, v163, v132
	v_cvt_pk_bf16_f32 v192, v192, v193
	s_waitcnt lgkmcnt(10)
	v_mfma_f32_16x16x32_bf16 v[78:81], v[178:181], v[106:109], v[78:81]
	v_mfma_f32_16x16x32_bf16 v[94:97], v[178:181], v[122:125], v[94:97]
	ds_read_b64_tr_b16 v[178:179], v243 offset:32768
	ds_read_b64_tr_b16 v[180:181], v243 offset:36864
	v_cvt_pk_bf16_f32 v193, v194, v195
	v_cvt_pk_bf16_f32 v194, v196, v197
	v_cvt_pk_bf16_f32 v195, v198, v199
	s_waitcnt lgkmcnt(11)
	v_mfma_f32_16x16x32_bf16 v[66:69], v[224:227], v[110:113], v[66:69]
	v_mfma_f32_16x16x32_bf16 v[82:85], v[224:227], v[126:129], v[82:85]
	ds_read_b64_tr_b16 v[224:225], v244 offset:32768
	ds_read_b64_tr_b16 v[226:227], v244 offset:36864
	v_cvt_pk_bf16_f32 v200, v200, v201
	v_cvt_pk_bf16_f32 v201, v202, v203
	v_cvt_pk_bf16_f32 v202, v204, v205
	s_waitcnt lgkmcnt(12)
	v_mfma_f32_16x16x32_bf16 v[70:73], v[228:231], v[110:113], v[70:73]
	v_mfma_f32_16x16x32_bf16 v[86:89], v[228:231], v[126:129], v[86:89]
	ds_read_b64_tr_b16 v[228:229], v245 offset:32768
	ds_read_b64_tr_b16 v[230:231], v245 offset:36864
	v_cvt_pk_bf16_f32 v203, v206, v207
	v_cvt_pk_bf16_f32 v208, v208, v209
	v_cvt_pk_bf16_f32 v209, v210, v211
	s_waitcnt lgkmcnt(13)
	v_mfma_f32_16x16x32_bf16 v[74:77], v[232:235], v[110:113], v[74:77]
	v_mfma_f32_16x16x32_bf16 v[90:93], v[232:235], v[126:129], v[90:93]
	v_cvt_pk_bf16_f32 v210, v212, v213
	v_cvt_pk_bf16_f32 v211, v214, v215
	v_cvt_pk_bf16_f32 v216, v216, v217
	s_waitcnt lgkmcnt(12)
	v_mfma_f32_16x16x32_bf16 v[78:81], v[236:239], v[110:113], v[78:81]
	v_mfma_f32_16x16x32_bf16 v[94:97], v[236:239], v[126:129], v[94:97]
	v_cvt_pk_bf16_f32 v217, v218, v219
	v_cvt_pk_bf16_f32 v218, v220, v221
	v_cvt_pk_bf16_f32 v219, v222, v223
	s_waitcnt lgkmcnt(10)
	v_mfma_f32_16x16x32_bf16 v[2:5], v[192:195], v[166:169], v[2:5]
	v_mfma_f32_16x16x32_bf16 v[34:37], v[208:211], v[166:169], v[34:37]
	ds_read_b64_tr_b16 v[232:233], v246 offset:32768
	ds_read_b64_tr_b16 v[234:235], v246 offset:36864
	s_waitcnt lgkmcnt(10)
	v_mfma_f32_16x16x32_bf16 v[6:9], v[192:195], v[170:173], v[6:9]
	v_mfma_f32_16x16x32_bf16 v[38:41], v[208:211], v[170:173], v[38:41]
	ds_read_b64_tr_b16 v[236:237], v247 offset:32768
	ds_read_b64_tr_b16 v[238:239], v247 offset:36864
	s_waitcnt lgkmcnt(10)
	v_mfma_f32_16x16x32_bf16 v[10:13], v[192:195], v[174:177], v[10:13]
	v_mfma_f32_16x16x32_bf16 v[42:45], v[208:211], v[174:177], v[42:45]
	ds_read_b64_tr_b16 v[166:167], v240 offset:40960
	ds_read_b64_tr_b16 v[168:169], v240 offset:45056
	v_exp_f32_e32 v66, v66
	v_exp_f32_e32 v67, v67
	v_exp_f32_e32 v68, v68
	s_waitcnt lgkmcnt(10)
	v_mfma_f32_16x16x32_bf16 v[14:17], v[192:195], v[178:181], v[14:17]
	v_mfma_f32_16x16x32_bf16 v[46:49], v[208:211], v[178:181], v[46:49]
	ds_read_b64_tr_b16 v[170:171], v241 offset:40960
	ds_read_b64_tr_b16 v[172:173], v241 offset:45056
	v_exp_f32_e32 v69, v69
	v_exp_f32_e32 v82, v82
	s_waitcnt lgkmcnt(10)
	v_mfma_f32_16x16x32_bf16 v[18:21], v[192:195], v[224:227], v[18:21]
	v_mfma_f32_16x16x32_bf16 v[50:53], v[208:211], v[224:227], v[50:53]
	ds_read_b64_tr_b16 v[174:175], v242 offset:40960
	ds_read_b64_tr_b16 v[176:177], v242 offset:45056
	v_exp_f32_e32 v83, v83
	v_exp_f32_e32 v84, v84
	s_waitcnt lgkmcnt(10)
	v_mfma_f32_16x16x32_bf16 v[22:25], v[192:195], v[228:231], v[22:25]
	v_mfma_f32_16x16x32_bf16 v[54:57], v[208:211], v[228:231], v[54:57]
	ds_read_b64_tr_b16 v[178:179], v243 offset:40960
	ds_read_b64_tr_b16 v[180:181], v243 offset:45056
	v_exp_f32_e32 v85, v85
	v_exp_f32_e32 v70, v70
	v_exp_f32_e32 v71, v71
	s_waitcnt lgkmcnt(10)
	v_mfma_f32_16x16x32_bf16 v[26:29], v[192:195], v[232:235], v[26:29]
	v_mfma_f32_16x16x32_bf16 v[58:61], v[208:211], v[232:235], v[58:61]
	ds_read_b64_tr_b16 v[224:225], v244 offset:40960
	ds_read_b64_tr_b16 v[226:227], v244 offset:45056
	v_exp_f32_e32 v72, v72
	v_exp_f32_e32 v73, v73
	s_waitcnt lgkmcnt(10)
	v_mfma_f32_16x16x32_bf16 v[30:33], v[192:195], v[236:239], v[30:33]
	v_mfma_f32_16x16x32_bf16 v[62:65], v[208:211], v[236:239], v[62:65]
	ds_read_b64_tr_b16 v[228:229], v245 offset:40960
	ds_read_b64_tr_b16 v[230:231], v245 offset:45056
	v_exp_f32_e32 v86, v86
	v_exp_f32_e32 v87, v87
	s_waitcnt lgkmcnt(10)
	v_mfma_f32_16x16x32_bf16 v[2:5], v[200:203], v[166:169], v[2:5]
	v_mfma_f32_16x16x32_bf16 v[34:37], v[216:219], v[166:169], v[34:37]
	ds_read_b64_tr_b16 v[232:233], v246 offset:40960
	ds_read_b64_tr_b16 v[234:235], v246 offset:45056
	ds_read_b128 v[166:169], v187 offset:49152
	v_exp_f32_e32 v88, v88
	v_exp_f32_e32 v89, v89
	s_waitcnt lgkmcnt(11)
	v_mfma_f32_16x16x32_bf16 v[6:9], v[200:203], v[170:173], v[6:9]
	v_mfma_f32_16x16x32_bf16 v[38:41], v[216:219], v[170:173], v[38:41]
	ds_read_b64_tr_b16 v[236:237], v247 offset:40960
	ds_read_b64_tr_b16 v[238:239], v247 offset:45056
	ds_read_b128 v[170:173], v187 offset:53248
	v_exp_f32_e32 v74, v74
	v_exp_f32_e32 v75, v75
	v_exp_f32_e32 v76, v76
	s_waitcnt lgkmcnt(12)
	v_mfma_f32_16x16x32_bf16 v[10:13], v[200:203], v[174:177], v[10:13]
	v_mfma_f32_16x16x32_bf16 v[42:45], v[216:219], v[174:177], v[42:45]
	ds_read_b128 v[174:177], v187 offset:57344
	v_exp_f32_e32 v77, v77
	v_exp_f32_e32 v90, v90
	s_waitcnt lgkmcnt(11)
	v_mfma_f32_16x16x32_bf16 v[14:17], v[200:203], v[178:181], v[14:17]
	v_mfma_f32_16x16x32_bf16 v[46:49], v[216:219], v[178:181], v[46:49]
	ds_read_b128 v[178:181], v187 offset:61440
	v_exp_f32_e32 v91, v91
	v_exp_f32_e32 v92, v92
	s_waitcnt lgkmcnt(10)
	v_mfma_f32_16x16x32_bf16 v[18:21], v[200:203], v[224:227], v[18:21]
	v_mfma_f32_16x16x32_bf16 v[50:53], v[216:219], v[224:227], v[50:53]
	ds_read_b128 v[224:227], v188 offset:49152
	v_exp_f32_e32 v93, v93
	v_exp_f32_e32 v78, v78
	v_exp_f32_e32 v79, v79
	s_waitcnt lgkmcnt(9)
	v_mfma_f32_16x16x32_bf16 v[22:25], v[200:203], v[228:231], v[22:25]
	v_mfma_f32_16x16x32_bf16 v[54:57], v[216:219], v[228:231], v[54:57]
	ds_read_b128 v[228:231], v188 offset:53248
	v_exp_f32_e32 v80, v80
	v_exp_f32_e32 v81, v81
	s_waitcnt lgkmcnt(8)
	v_mfma_f32_16x16x32_bf16 v[26:29], v[200:203], v[232:235], v[26:29]
	v_mfma_f32_16x16x32_bf16 v[58:61], v[216:219], v[232:235], v[58:61]
	ds_read_b128 v[232:235], v188 offset:57344
	v_exp_f32_e32 v94, v94
	v_exp_f32_e32 v95, v95
	s_waitcnt lgkmcnt(6)
	v_mfma_f32_16x16x32_bf16 v[30:33], v[200:203], v[236:239], v[30:33]
	v_mfma_f32_16x16x32_bf16 v[62:65], v[216:219], v[236:239], v[62:65]
	ds_read_b128 v[236:239], v188 offset:61440
	v_exp_f32_e32 v96, v96
	v_exp_f32_e32 v97, v97
	s_waitcnt vmcnt(0)
	s_barrier
	v_mfma_f32_16x16x32_bf16 v[192:195], v[166:169], v[98:101], 0
	v_mfma_f32_16x16x32_bf16 v[208:211], v[166:169], v[114:117], 0
	ds_read_b128 v[166:169], v189 offset:49152
	s_add_i32 m0, s45, 0x8000
	v_add_f32_e32 v130, v66, v67
	v_add_f32_e32 v131, v68, v69
	v_add_f32_e32 v130, v70, v130
	global_load_lds_dwordx4 v152, s[64:65]
	s_waitcnt lgkmcnt(7)
	v_mfma_f32_16x16x32_bf16 v[196:199], v[170:173], v[98:101], 0
	v_mfma_f32_16x16x32_bf16 v[212:215], v[170:173], v[114:117], 0
	ds_read_b128 v[170:173], v189 offset:53248
	s_add_i32 m0, s45, 0xc000
	v_add_f32_e32 v131, v71, v131
	v_add_f32_e32 v130, v72, v130
	v_add_f32_e32 v131, v73, v131
	global_load_lds_dwordx4 v150, s[62:63]
	s_waitcnt lgkmcnt(7)
	v_mfma_f32_16x16x32_bf16 v[200:203], v[174:177], v[98:101], 0
	v_mfma_f32_16x16x32_bf16 v[216:219], v[174:177], v[114:117], 0
	ds_read_b128 v[174:177], v189 offset:57344
	s_add_i32 m0, s45, 0xa000
	v_add_f32_e32 v130, v74, v130
	v_add_f32_e32 v131, v75, v131
	v_add_f32_e32 v130, v76, v130
	global_load_lds_dwordx4 v153, s[64:65]
	s_waitcnt lgkmcnt(7)
	v_mfma_f32_16x16x32_bf16 v[204:207], v[178:181], v[98:101], 0
	v_mfma_f32_16x16x32_bf16 v[220:223], v[178:181], v[114:117], 0
	ds_read_b128 v[178:181], v189 offset:61440
	s_add_i32 m0, s45, 0xe000
	v_add_f32_e32 v131, v77, v131
	v_add_f32_e32 v130, v78, v130
	v_add_f32_e32 v131, v79, v131
	global_load_lds_dwordx4 v151, s[62:63]
	s_add_u32 s62, s62, 0x4000
	s_addc_u32 s63, s63, 0
	s_add_u32 s64, s64, 0x4000
	s_addc_u32 s65, s65, 0
	s_waitcnt lgkmcnt(7)
	v_mfma_f32_16x16x32_bf16 v[192:195], v[224:227], v[102:105], v[192:195]
	v_mfma_f32_16x16x32_bf16 v[208:211], v[224:227], v[118:121], v[208:211]
	ds_read_b128 v[224:227], v190 offset:49152
	v_add_f32_e32 v130, v80, v130
	v_add_f32_e32 v131, v81, v131
	v_add_f32_e32 v130, v130, v131
	s_waitcnt lgkmcnt(7)
	v_mfma_f32_16x16x32_bf16 v[196:199], v[228:231], v[102:105], v[196:199]
	v_mfma_f32_16x16x32_bf16 v[212:215], v[228:231], v[118:121], v[212:215]
	ds_read_b128 v[228:231], v190 offset:53248
	v_add_f32_e32 v165, v165, v130
	v_add_f32_e32 v132, v82, v83
	v_add_f32_e32 v133, v84, v85
	s_waitcnt lgkmcnt(7)
	v_mfma_f32_16x16x32_bf16 v[200:203], v[232:235], v[102:105], v[200:203]
	v_mfma_f32_16x16x32_bf16 v[216:219], v[232:235], v[118:121], v[216:219]
	ds_read_b128 v[232:235], v190 offset:57344
	v_add_f32_e32 v132, v86, v132
	v_add_f32_e32 v133, v87, v133
	v_add_f32_e32 v132, v88, v132
	s_waitcnt lgkmcnt(7)
	v_mfma_f32_16x16x32_bf16 v[204:207], v[236:239], v[102:105], v[204:207]
	v_mfma_f32_16x16x32_bf16 v[220:223], v[236:239], v[118:121], v[220:223]
	ds_read_b128 v[236:239], v190 offset:61440
	v_add_f32_e32 v133, v89, v133
	v_add_f32_e32 v132, v90, v132
	v_add_f32_e32 v133, v91, v133
	s_waitcnt lgkmcnt(7)
	v_mfma_f32_16x16x32_bf16 v[192:195], v[166:169], v[106:109], v[192:195]
	v_mfma_f32_16x16x32_bf16 v[208:211], v[166:169], v[122:125], v[208:211]
	ds_read_b64_tr_b16 v[166:167], v142 offset:0
	ds_read_b64_tr_b16 v[168:169], v142 offset:4096
	v_add_f32_e32 v132, v92, v132
	v_add_f32_e32 v133, v93, v133
	v_add_f32_e32 v132, v94, v132
	s_waitcnt lgkmcnt(8)
	v_mfma_f32_16x16x32_bf16 v[196:199], v[170:173], v[106:109], v[196:199]
	v_mfma_f32_16x16x32_bf16 v[212:215], v[170:173], v[122:125], v[212:215]
	ds_read_b64_tr_b16 v[170:171], v143 offset:0
	ds_read_b64_tr_b16 v[172:173], v143 offset:4096
	v_add_f32_e32 v133, v95, v133
	v_add_f32_e32 v132, v96, v132
	v_add_f32_e32 v133, v97, v133
	s_waitcnt lgkmcnt(9)
	v_mfma_f32_16x16x32_bf16 v[200:203], v[174:177], v[106:109], v[200:203]
	v_mfma_f32_16x16x32_bf16 v[216:219], v[174:177], v[122:125], v[216:219]
	ds_read_b64_tr_b16 v[174:175], v144 offset:0
	ds_read_b64_tr_b16 v[176:177], v144 offset:4096
	v_add_f32_e32 v132, v132, v133
	v_add_f32_e32 v163, v163, v132
	v_cvt_pk_bf16_f32 v66, v66, v67
	s_waitcnt lgkmcnt(10)
	v_mfma_f32_16x16x32_bf16 v[204:207], v[178:181], v[106:109], v[204:207]
	v_mfma_f32_16x16x32_bf16 v[220:223], v[178:181], v[122:125], v[220:223]
	ds_read_b64_tr_b16 v[178:179], v145 offset:0
	ds_read_b64_tr_b16 v[180:181], v145 offset:4096
	v_cvt_pk_bf16_f32 v67, v68, v69
	v_cvt_pk_bf16_f32 v68, v70, v71
	v_cvt_pk_bf16_f32 v69, v72, v73
	s_waitcnt lgkmcnt(11)
	v_mfma_f32_16x16x32_bf16 v[192:195], v[224:227], v[110:113], v[192:195]
	v_mfma_f32_16x16x32_bf16 v[208:211], v[224:227], v[126:129], v[208:211]
	ds_read_b64_tr_b16 v[224:225], v146 offset:0
	ds_read_b64_tr_b16 v[226:227], v146 offset:4096
	v_cvt_pk_bf16_f32 v74, v74, v75
	v_cvt_pk_bf16_f32 v75, v76, v77
	v_cvt_pk_bf16_f32 v76, v78, v79
	s_waitcnt lgkmcnt(12)
	v_mfma_f32_16x16x32_bf16 v[196:199], v[228:231], v[110:113], v[196:199]
	v_mfma_f32_16x16x32_bf16 v[212:215], v[228:231], v[126:129], v[212:215]
	ds_read_b64_tr_b16 v[228:229], v147 offset:0
	ds_read_b64_tr_b16 v[230:231], v147 offset:4096
	v_cvt_pk_bf16_f32 v77, v80, v81
	v_cvt_pk_bf16_f32 v82, v82, v83
	v_cvt_pk_bf16_f32 v83, v84, v85
	s_waitcnt lgkmcnt(13)
	v_mfma_f32_16x16x32_bf16 v[200:203], v[232:235], v[110:113], v[200:203]
	v_mfma_f32_16x16x32_bf16 v[216:219], v[232:235], v[126:129], v[216:219]
	v_cvt_pk_bf16_f32 v84, v86, v87
	v_cvt_pk_bf16_f32 v85, v88, v89
	v_cvt_pk_bf16_f32 v90, v90, v91
	s_waitcnt lgkmcnt(12)
	v_mfma_f32_16x16x32_bf16 v[204:207], v[236:239], v[110:113], v[204:207]
	v_mfma_f32_16x16x32_bf16 v[220:223], v[236:239], v[126:129], v[220:223]
	v_cvt_pk_bf16_f32 v91, v92, v93
	v_cvt_pk_bf16_f32 v92, v94, v95
	v_cvt_pk_bf16_f32 v93, v96, v97
	s_waitcnt lgkmcnt(10)
	v_mfma_f32_16x16x32_bf16 v[2:5], v[66:69], v[166:169], v[2:5]
	v_mfma_f32_16x16x32_bf16 v[34:37], v[82:85], v[166:169], v[34:37]
	ds_read_b64_tr_b16 v[232:233], v148 offset:0
	ds_read_b64_tr_b16 v[234:235], v148 offset:4096
	s_waitcnt lgkmcnt(10)
	v_mfma_f32_16x16x32_bf16 v[6:9], v[66:69], v[170:173], v[6:9]
	v_mfma_f32_16x16x32_bf16 v[38:41], v[82:85], v[170:173], v[38:41]
	ds_read_b64_tr_b16 v[236:237], v149 offset:0
	ds_read_b64_tr_b16 v[238:239], v149 offset:4096
	s_waitcnt lgkmcnt(10)
	v_mfma_f32_16x16x32_bf16 v[10:13], v[66:69], v[174:177], v[10:13]
	v_mfma_f32_16x16x32_bf16 v[42:45], v[82:85], v[174:177], v[42:45]
	ds_read_b64_tr_b16 v[166:167], v142 offset:8192
	ds_read_b64_tr_b16 v[168:169], v142 offset:12288
	v_exp_f32_e32 v192, v192
	v_exp_f32_e32 v193, v193
	v_exp_f32_e32 v194, v194
	s_waitcnt lgkmcnt(10)
	v_mfma_f32_16x16x32_bf16 v[14:17], v[66:69], v[178:181], v[14:17]
	v_mfma_f32_16x16x32_bf16 v[46:49], v[82:85], v[178:181], v[46:49]
	ds_read_b64_tr_b16 v[170:171], v143 offset:8192
	ds_read_b64_tr_b16 v[172:173], v143 offset:12288
	v_exp_f32_e32 v195, v195
	v_exp_f32_e32 v208, v208
	s_waitcnt lgkmcnt(10)
	v_mfma_f32_16x16x32_bf16 v[18:21], v[66:69], v[224:227], v[18:21]
	v_mfma_f32_16x16x32_bf16 v[50:53], v[82:85], v[224:227], v[50:53]
	ds_read_b64_tr_b16 v[174:175], v144 offset:8192
	ds_read_b64_tr_b16 v[176:177], v144 offset:12288
	v_exp_f32_e32 v209, v209
	v_exp_f32_e32 v210, v210
	s_waitcnt lgkmcnt(10)
	v_mfma_f32_16x16x32_bf16 v[22:25], v[66:69], v[228:231], v[22:25]
	v_mfma_f32_16x16x32_bf16 v[54:57], v[82:85], v[228:231], v[54:57]
	ds_read_b64_tr_b16 v[178:179], v145 offset:8192
	ds_read_b64_tr_b16 v[180:181], v145 offset:12288
	v_exp_f32_e32 v211, v211
	v_exp_f32_e32 v196, v196
	v_exp_f32_e32 v197, v197
	s_waitcnt lgkmcnt(10)
	v_mfma_f32_16x16x32_bf16 v[26:29], v[66:69], v[232:235], v[26:29]
	v_mfma_f32_16x16x32_bf16 v[58:61], v[82:85], v[232:235], v[58:61]
	ds_read_b64_tr_b16 v[224:225], v146 offset:8192
	ds_read_b64_tr_b16 v[226:227], v146 offset:12288
	v_exp_f32_e32 v198, v198
	v_exp_f32_e32 v199, v199
	s_waitcnt lgkmcnt(10)
	v_mfma_f32_16x16x32_bf16 v[30:33], v[66:69], v[236:239], v[30:33]
	v_mfma_f32_16x16x32_bf16 v[62:65], v[82:85], v[236:239], v[62:65]
	ds_read_b64_tr_b16 v[228:229], v147 offset:8192
	ds_read_b64_tr_b16 v[230:231], v147 offset:12288
	v_exp_f32_e32 v212, v212
	v_exp_f32_e32 v213, v213
	s_waitcnt lgkmcnt(10)
	v_mfma_f32_16x16x32_bf16 v[2:5], v[74:77], v[166:169], v[2:5]
	v_mfma_f32_16x16x32_bf16 v[34:37], v[90:93], v[166:169], v[34:37]
	ds_read_b64_tr_b16 v[232:233], v148 offset:8192
	ds_read_b64_tr_b16 v[234:235], v148 offset:12288
	ds_read_b128 v[166:169], v183 offset:16384
	v_exp_f32_e32 v214, v214
	v_exp_f32_e32 v215, v215
	s_waitcnt lgkmcnt(11)
	v_mfma_f32_16x16x32_bf16 v[6:9], v[74:77], v[170:173], v[6:9]
	v_mfma_f32_16x16x32_bf16 v[38:41], v[90:93], v[170:173], v[38:41]
	ds_read_b64_tr_b16 v[236:237], v149 offset:8192
	ds_read_b64_tr_b16 v[238:239], v149 offset:12288
	ds_read_b128 v[170:173], v183 offset:20480
	v_exp_f32_e32 v200, v200
	v_exp_f32_e32 v201, v201
	v_exp_f32_e32 v202, v202
	s_waitcnt lgkmcnt(12)
	v_mfma_f32_16x16x32_bf16 v[10:13], v[74:77], v[174:177], v[10:13]
	v_mfma_f32_16x16x32_bf16 v[42:45], v[90:93], v[174:177], v[42:45]
	ds_read_b128 v[174:177], v183 offset:24576
	v_exp_f32_e32 v203, v203
	v_exp_f32_e32 v216, v216
	s_waitcnt lgkmcnt(11)
	v_mfma_f32_16x16x32_bf16 v[14:17], v[74:77], v[178:181], v[14:17]
	v_mfma_f32_16x16x32_bf16 v[46:49], v[90:93], v[178:181], v[46:49]
	ds_read_b128 v[178:181], v183 offset:28672
	v_exp_f32_e32 v217, v217
	v_exp_f32_e32 v218, v218
	s_waitcnt lgkmcnt(10)
	v_mfma_f32_16x16x32_bf16 v[18:21], v[74:77], v[224:227], v[18:21]
	v_mfma_f32_16x16x32_bf16 v[50:53], v[90:93], v[224:227], v[50:53]
	ds_read_b128 v[224:227], v184 offset:16384
	v_exp_f32_e32 v219, v219
	v_exp_f32_e32 v204, v204
	v_exp_f32_e32 v205, v205
	s_waitcnt lgkmcnt(9)
	v_mfma_f32_16x16x32_bf16 v[22:25], v[74:77], v[228:231], v[22:25]
	v_mfma_f32_16x16x32_bf16 v[54:57], v[90:93], v[228:231], v[54:57]
	ds_read_b128 v[228:231], v184 offset:20480
	v_exp_f32_e32 v206, v206
	v_exp_f32_e32 v207, v207
	s_waitcnt lgkmcnt(8)
	v_mfma_f32_16x16x32_bf16 v[26:29], v[74:77], v[232:235], v[26:29]
	v_mfma_f32_16x16x32_bf16 v[58:61], v[90:93], v[232:235], v[58:61]
	ds_read_b128 v[232:235], v184 offset:24576
	v_exp_f32_e32 v220, v220
	v_exp_f32_e32 v221, v221
	s_waitcnt lgkmcnt(6)
	v_mfma_f32_16x16x32_bf16 v[30:33], v[74:77], v[236:239], v[30:33]
	v_mfma_f32_16x16x32_bf16 v[62:65], v[90:93], v[236:239], v[62:65]
	ds_read_b128 v[236:239], v184 offset:28672
	v_exp_f32_e32 v222, v222
	v_exp_f32_e32 v223, v223
	s_waitcnt vmcnt(0)
	s_barrier
	v_mfma_f32_16x16x32_bf16 v[66:69], v[166:169], v[98:101], 0
	v_mfma_f32_16x16x32_bf16 v[82:85], v[166:169], v[114:117], 0
	ds_read_b128 v[166:169], v185 offset:16384
	s_add_i32 m0, s45, 0x10000
	v_add_f32_e32 v130, v192, v193
	v_add_f32_e32 v131, v194, v195
	v_add_f32_e32 v130, v196, v130
	global_load_lds_dwordx4 v152, s[64:65]
	s_waitcnt lgkmcnt(7)
	v_mfma_f32_16x16x32_bf16 v[70:73], v[170:173], v[98:101], 0
	v_mfma_f32_16x16x32_bf16 v[86:89], v[170:173], v[114:117], 0
	ds_read_b128 v[170:173], v185 offset:20480
	s_add_i32 m0, s45, 0x14000
	v_add_f32_e32 v131, v197, v131
	v_add_f32_e32 v130, v198, v130
	v_add_f32_e32 v131, v199, v131
	global_load_lds_dwordx4 v150, s[62:63]
	s_waitcnt lgkmcnt(7)
	v_mfma_f32_16x16x32_bf16 v[74:77], v[174:177], v[98:101], 0
	v_mfma_f32_16x16x32_bf16 v[90:93], v[174:177], v[114:117], 0
	ds_read_b128 v[174:177], v185 offset:24576
	s_add_i32 m0, s45, 0x12000
	v_add_f32_e32 v130, v200, v130
	v_add_f32_e32 v131, v201, v131
	v_add_f32_e32 v130, v202, v130
	global_load_lds_dwordx4 v153, s[64:65]
	s_waitcnt lgkmcnt(7)
	v_mfma_f32_16x16x32_bf16 v[78:81], v[178:181], v[98:101], 0
	v_mfma_f32_16x16x32_bf16 v[94:97], v[178:181], v[114:117], 0
	ds_read_b128 v[178:181], v185 offset:28672
	s_add_i32 m0, s45, 0x16000
	v_add_f32_e32 v131, v203, v131
	v_add_f32_e32 v130, v204, v130
	v_add_f32_e32 v131, v205, v131
	global_load_lds_dwordx4 v151, s[62:63]
	s_add_u32 s62, s62, 0x4000
	s_addc_u32 s63, s63, 0
	s_add_u32 s64, s64, 0x4000
	s_addc_u32 s65, s65, 0
	s_waitcnt lgkmcnt(7)
	v_mfma_f32_16x16x32_bf16 v[66:69], v[224:227], v[102:105], v[66:69]
	v_mfma_f32_16x16x32_bf16 v[82:85], v[224:227], v[118:121], v[82:85]
	ds_read_b128 v[224:227], v186 offset:16384
	v_add_f32_e32 v130, v206, v130
	v_add_f32_e32 v131, v207, v131
	v_add_f32_e32 v130, v130, v131
	s_waitcnt lgkmcnt(7)
	v_mfma_f32_16x16x32_bf16 v[70:73], v[228:231], v[102:105], v[70:73]
	v_mfma_f32_16x16x32_bf16 v[86:89], v[228:231], v[118:121], v[86:89]
	ds_read_b128 v[228:231], v186 offset:20480
	v_add_f32_e32 v165, v165, v130
	v_add_f32_e32 v132, v208, v209
	v_add_f32_e32 v133, v210, v211
	s_waitcnt lgkmcnt(7)
	v_mfma_f32_16x16x32_bf16 v[74:77], v[232:235], v[102:105], v[74:77]
	v_mfma_f32_16x16x32_bf16 v[90:93], v[232:235], v[118:121], v[90:93]
	ds_read_b128 v[232:235], v186 offset:24576
	v_add_f32_e32 v132, v212, v132
	v_add_f32_e32 v133, v213, v133
	v_add_f32_e32 v132, v214, v132
	s_waitcnt lgkmcnt(7)
	v_mfma_f32_16x16x32_bf16 v[78:81], v[236:239], v[102:105], v[78:81]
	v_mfma_f32_16x16x32_bf16 v[94:97], v[236:239], v[118:121], v[94:97]
	ds_read_b128 v[236:239], v186 offset:28672
	v_add_f32_e32 v133, v215, v133
	v_add_f32_e32 v132, v216, v132
	v_add_f32_e32 v133, v217, v133
	s_waitcnt lgkmcnt(7)
	v_mfma_f32_16x16x32_bf16 v[66:69], v[166:169], v[106:109], v[66:69]
	v_mfma_f32_16x16x32_bf16 v[82:85], v[166:169], v[122:125], v[82:85]
	ds_read_b64_tr_b16 v[166:167], v142 offset:32768
	ds_read_b64_tr_b16 v[168:169], v142 offset:36864
	v_add_f32_e32 v132, v218, v132
	v_add_f32_e32 v133, v219, v133
	v_add_f32_e32 v132, v220, v132
	s_waitcnt lgkmcnt(8)
	v_mfma_f32_16x16x32_bf16 v[70:73], v[170:173], v[106:109], v[70:73]
	v_mfma_f32_16x16x32_bf16 v[86:89], v[170:173], v[122:125], v[86:89]
	ds_read_b64_tr_b16 v[170:171], v143 offset:32768
	ds_read_b64_tr_b16 v[172:173], v143 offset:36864
	v_add_f32_e32 v133, v221, v133
	v_add_f32_e32 v132, v222, v132
	v_add_f32_e32 v133, v223, v133
	s_waitcnt lgkmcnt(9)
	v_mfma_f32_16x16x32_bf16 v[74:77], v[174:177], v[106:109], v[74:77]
	v_mfma_f32_16x16x32_bf16 v[90:93], v[174:177], v[122:125], v[90:93]
	ds_read_b64_tr_b16 v[174:175], v144 offset:32768
	ds_read_b64_tr_b16 v[176:177], v144 offset:36864
	v_add_f32_e32 v132, v132, v133
	v_add_f32_e32 v163, v163, v132
	v_cvt_pk_bf16_f32 v192, v192, v193
	s_waitcnt lgkmcnt(10)
	v_mfma_f32_16x16x32_bf16 v[78:81], v[178:181], v[106:109], v[78:81]
	v_mfma_f32_16x16x32_bf16 v[94:97], v[178:181], v[122:125], v[94:97]
	ds_read_b64_tr_b16 v[178:179], v145 offset:32768
	ds_read_b64_tr_b16 v[180:181], v145 offset:36864
	v_cvt_pk_bf16_f32 v193, v194, v195
	v_cvt_pk_bf16_f32 v194, v196, v197
	v_cvt_pk_bf16_f32 v195, v198, v199
	s_waitcnt lgkmcnt(11)
	v_mfma_f32_16x16x32_bf16 v[66:69], v[224:227], v[110:113], v[66:69]
	v_mfma_f32_16x16x32_bf16 v[82:85], v[224:227], v[126:129], v[82:85]
	ds_read_b64_tr_b16 v[224:225], v146 offset:32768
	ds_read_b64_tr_b16 v[226:227], v146 offset:36864
	v_cvt_pk_bf16_f32 v200, v200, v201
	v_cvt_pk_bf16_f32 v201, v202, v203
	v_cvt_pk_bf16_f32 v202, v204, v205
	s_waitcnt lgkmcnt(12)
	v_mfma_f32_16x16x32_bf16 v[70:73], v[228:231], v[110:113], v[70:73]
	v_mfma_f32_16x16x32_bf16 v[86:89], v[228:231], v[126:129], v[86:89]
	ds_read_b64_tr_b16 v[228:229], v147 offset:32768
	ds_read_b64_tr_b16 v[230:231], v147 offset:36864
	v_cvt_pk_bf16_f32 v203, v206, v207
	v_cvt_pk_bf16_f32 v208, v208, v209
	v_cvt_pk_bf16_f32 v209, v210, v211
	s_waitcnt lgkmcnt(13)
	v_mfma_f32_16x16x32_bf16 v[74:77], v[232:235], v[110:113], v[74:77]
	v_mfma_f32_16x16x32_bf16 v[90:93], v[232:235], v[126:129], v[90:93]
	v_cvt_pk_bf16_f32 v210, v212, v213
	v_cvt_pk_bf16_f32 v211, v214, v215
	v_cvt_pk_bf16_f32 v216, v216, v217
	s_waitcnt lgkmcnt(12)
	v_mfma_f32_16x16x32_bf16 v[78:81], v[236:239], v[110:113], v[78:81]
	v_mfma_f32_16x16x32_bf16 v[94:97], v[236:239], v[126:129], v[94:97]
	v_cvt_pk_bf16_f32 v217, v218, v219
	v_cvt_pk_bf16_f32 v218, v220, v221
	v_cvt_pk_bf16_f32 v219, v222, v223
	s_waitcnt lgkmcnt(10)
	v_mfma_f32_16x16x32_bf16 v[2:5], v[192:195], v[166:169], v[2:5]
	v_mfma_f32_16x16x32_bf16 v[34:37], v[208:211], v[166:169], v[34:37]
	ds_read_b64_tr_b16 v[232:233], v148 offset:32768
	ds_read_b64_tr_b16 v[234:235], v148 offset:36864
	s_waitcnt lgkmcnt(10)
	v_mfma_f32_16x16x32_bf16 v[6:9], v[192:195], v[170:173], v[6:9]
	v_mfma_f32_16x16x32_bf16 v[38:41], v[208:211], v[170:173], v[38:41]
	ds_read_b64_tr_b16 v[236:237], v149 offset:32768
	ds_read_b64_tr_b16 v[238:239], v149 offset:36864
	s_waitcnt lgkmcnt(10)
	v_mfma_f32_16x16x32_bf16 v[10:13], v[192:195], v[174:177], v[10:13]
	v_mfma_f32_16x16x32_bf16 v[42:45], v[208:211], v[174:177], v[42:45]
	ds_read_b64_tr_b16 v[166:167], v142 offset:40960
	ds_read_b64_tr_b16 v[168:169], v142 offset:45056
	v_exp_f32_e32 v66, v66
	v_exp_f32_e32 v67, v67
	v_exp_f32_e32 v68, v68
	s_waitcnt lgkmcnt(10)
	v_mfma_f32_16x16x32_bf16 v[14:17], v[192:195], v[178:181], v[14:17]
	v_mfma_f32_16x16x32_bf16 v[46:49], v[208:211], v[178:181], v[46:49]
	ds_read_b64_tr_b16 v[170:171], v143 offset:40960
	ds_read_b64_tr_b16 v[172:173], v143 offset:45056
	v_exp_f32_e32 v69, v69
	v_exp_f32_e32 v82, v82
	s_waitcnt lgkmcnt(10)
	v_mfma_f32_16x16x32_bf16 v[18:21], v[192:195], v[224:227], v[18:21]
	v_mfma_f32_16x16x32_bf16 v[50:53], v[208:211], v[224:227], v[50:53]
	ds_read_b64_tr_b16 v[174:175], v144 offset:40960
	ds_read_b64_tr_b16 v[176:177], v144 offset:45056
	v_exp_f32_e32 v83, v83
	v_exp_f32_e32 v84, v84
	s_waitcnt lgkmcnt(10)
	v_mfma_f32_16x16x32_bf16 v[22:25], v[192:195], v[228:231], v[22:25]
	v_mfma_f32_16x16x32_bf16 v[54:57], v[208:211], v[228:231], v[54:57]
	ds_read_b64_tr_b16 v[178:179], v145 offset:40960
	ds_read_b64_tr_b16 v[180:181], v145 offset:45056
	v_exp_f32_e32 v85, v85
	v_exp_f32_e32 v70, v70
	v_exp_f32_e32 v71, v71
	s_waitcnt lgkmcnt(10)
	v_mfma_f32_16x16x32_bf16 v[26:29], v[192:195], v[232:235], v[26:29]
	v_mfma_f32_16x16x32_bf16 v[58:61], v[208:211], v[232:235], v[58:61]
	ds_read_b64_tr_b16 v[224:225], v146 offset:40960
	ds_read_b64_tr_b16 v[226:227], v146 offset:45056
	v_exp_f32_e32 v72, v72
	v_exp_f32_e32 v73, v73
	s_waitcnt lgkmcnt(10)
	v_mfma_f32_16x16x32_bf16 v[30:33], v[192:195], v[236:239], v[30:33]
	v_mfma_f32_16x16x32_bf16 v[62:65], v[208:211], v[236:239], v[62:65]
	ds_read_b64_tr_b16 v[228:229], v147 offset:40960
	ds_read_b64_tr_b16 v[230:231], v147 offset:45056
	v_exp_f32_e32 v86, v86
	v_exp_f32_e32 v87, v87
	s_waitcnt lgkmcnt(10)
	v_mfma_f32_16x16x32_bf16 v[2:5], v[200:203], v[166:169], v[2:5]
	v_mfma_f32_16x16x32_bf16 v[34:37], v[216:219], v[166:169], v[34:37]
	ds_read_b64_tr_b16 v[232:233], v148 offset:40960
	ds_read_b64_tr_b16 v[234:235], v148 offset:45056
	ds_read_b128 v[166:169], v183 offset:49152
	v_exp_f32_e32 v88, v88
	v_exp_f32_e32 v89, v89
	s_waitcnt lgkmcnt(11)
	v_mfma_f32_16x16x32_bf16 v[6:9], v[200:203], v[170:173], v[6:9]
	v_mfma_f32_16x16x32_bf16 v[38:41], v[216:219], v[170:173], v[38:41]
	ds_read_b64_tr_b16 v[236:237], v149 offset:40960
	ds_read_b64_tr_b16 v[238:239], v149 offset:45056
	ds_read_b128 v[170:173], v183 offset:53248
	v_exp_f32_e32 v74, v74
	v_exp_f32_e32 v75, v75
	v_exp_f32_e32 v76, v76
	s_waitcnt lgkmcnt(12)
	v_mfma_f32_16x16x32_bf16 v[10:13], v[200:203], v[174:177], v[10:13]
	v_mfma_f32_16x16x32_bf16 v[42:45], v[216:219], v[174:177], v[42:45]
	ds_read_b128 v[174:177], v183 offset:57344
	v_exp_f32_e32 v77, v77
	v_exp_f32_e32 v90, v90
	s_waitcnt lgkmcnt(11)
	v_mfma_f32_16x16x32_bf16 v[14:17], v[200:203], v[178:181], v[14:17]
	v_mfma_f32_16x16x32_bf16 v[46:49], v[216:219], v[178:181], v[46:49]
	ds_read_b128 v[178:181], v183 offset:61440
	v_exp_f32_e32 v91, v91
	v_exp_f32_e32 v92, v92
	s_waitcnt lgkmcnt(10)
	v_mfma_f32_16x16x32_bf16 v[18:21], v[200:203], v[224:227], v[18:21]
	v_mfma_f32_16x16x32_bf16 v[50:53], v[216:219], v[224:227], v[50:53]
	ds_read_b128 v[224:227], v184 offset:49152
	v_exp_f32_e32 v93, v93
	v_exp_f32_e32 v78, v78
	v_exp_f32_e32 v79, v79
	s_waitcnt lgkmcnt(9)
	v_mfma_f32_16x16x32_bf16 v[22:25], v[200:203], v[228:231], v[22:25]
	v_mfma_f32_16x16x32_bf16 v[54:57], v[216:219], v[228:231], v[54:57]
	ds_read_b128 v[228:231], v184 offset:53248
	v_exp_f32_e32 v80, v80
	v_exp_f32_e32 v81, v81
	s_waitcnt lgkmcnt(8)
	v_mfma_f32_16x16x32_bf16 v[26:29], v[200:203], v[232:235], v[26:29]
	v_mfma_f32_16x16x32_bf16 v[58:61], v[216:219], v[232:235], v[58:61]
	ds_read_b128 v[232:235], v184 offset:57344
	v_exp_f32_e32 v94, v94
	v_exp_f32_e32 v95, v95
	s_waitcnt lgkmcnt(6)
	v_mfma_f32_16x16x32_bf16 v[30:33], v[200:203], v[236:239], v[30:33]
	v_mfma_f32_16x16x32_bf16 v[62:65], v[216:219], v[236:239], v[62:65]
	ds_read_b128 v[236:239], v184 offset:61440
	v_exp_f32_e32 v96, v96
	v_exp_f32_e32 v97, v97
	s_waitcnt vmcnt(0)
	s_barrier
	s_sub_u32 s66, s66, 1
	s_cmp_lg_u32 s66, 0
	s_cbranch_scc1 .Lattn_loop
	v_mfma_f32_16x16x32_bf16 v[192:195], v[166:169], v[98:101], 0
	v_mfma_f32_16x16x32_bf16 v[208:211], v[166:169], v[114:117], 0
	ds_read_b128 v[166:169], v185 offset:49152
	s_add_i32 m0, s45, 0x18000
	v_add_f32_e32 v130, v66, v67
	v_add_f32_e32 v131, v68, v69
	v_add_f32_e32 v130, v70, v130
	global_load_lds_dwordx4 v152, s[64:65]
	s_waitcnt lgkmcnt(7)
	v_mfma_f32_16x16x32_bf16 v[196:199], v[170:173], v[98:101], 0
	v_mfma_f32_16x16x32_bf16 v[212:215], v[170:173], v[114:117], 0
	ds_read_b128 v[170:173], v185 offset:53248
	s_add_i32 m0, s45, 0x1c000
	v_add_f32_e32 v131, v71, v131
	v_add_f32_e32 v130, v72, v130
	v_add_f32_e32 v131, v73, v131
	global_load_lds_dwordx4 v150, s[62:63]
	s_waitcnt lgkmcnt(7)
	v_mfma_f32_16x16x32_bf16 v[200:203], v[174:177], v[98:101], 0
	v_mfma_f32_16x16x32_bf16 v[216:219], v[174:177], v[114:117], 0
	ds_read_b128 v[174:177], v185 offset:57344
	s_add_i32 m0, s45, 0x1a000
	v_add_f32_e32 v130, v74, v130
	v_add_f32_e32 v131, v75, v131
	v_add_f32_e32 v130, v76, v130
	global_load_lds_dwordx4 v153, s[64:65]
	s_waitcnt lgkmcnt(7)
	v_mfma_f32_16x16x32_bf16 v[204:207], v[178:181], v[98:101], 0
	v_mfma_f32_16x16x32_bf16 v[220:223], v[178:181], v[114:117], 0
	ds_read_b128 v[178:181], v185 offset:61440
	s_add_i32 m0, s45, 0x1e000
	v_add_f32_e32 v131, v77, v131
	v_add_f32_e32 v130, v78, v130
	v_add_f32_e32 v131, v79, v131
	global_load_lds_dwordx4 v151, s[62:63]
	s_add_u32 s62, s62, 0x4000
	s_addc_u32 s63, s63, 0
	s_add_u32 s64, s64, 0x4000
	s_addc_u32 s65, s65, 0
	s_waitcnt lgkmcnt(7)
	v_mfma_f32_16x16x32_bf16 v[192:195], v[224:227], v[102:105], v[192:195]
	v_mfma_f32_16x16x32_bf16 v[208:211], v[224:227], v[118:121], v[208:211]
	ds_read_b128 v[224:227], v186 offset:49152
	v_add_f32_e32 v130, v80, v130
	v_add_f32_e32 v131, v81, v131
	v_add_f32_e32 v130, v130, v131
	s_waitcnt lgkmcnt(7)
	v_mfma_f32_16x16x32_bf16 v[196:199], v[228:231], v[102:105], v[196:199]
	v_mfma_f32_16x16x32_bf16 v[212:215], v[228:231], v[118:121], v[212:215]
	ds_read_b128 v[228:231], v186 offset:53248
	v_add_f32_e32 v165, v165, v130
	v_add_f32_e32 v132, v82, v83
	v_add_f32_e32 v133, v84, v85
	s_waitcnt lgkmcnt(7)
	v_mfma_f32_16x16x32_bf16 v[200:203], v[232:235], v[102:105], v[200:203]
	v_mfma_f32_16x16x32_bf16 v[216:219], v[232:235], v[118:121], v[216:219]
	ds_read_b128 v[232:235], v186 offset:57344
	v_add_f32_e32 v132, v86, v132
	v_add_f32_e32 v133, v87, v133
	v_add_f32_e32 v132, v88, v132
	s_waitcnt lgkmcnt(7)
	v_mfma_f32_16x16x32_bf16 v[204:207], v[236:239], v[102:105], v[204:207]
	v_mfma_f32_16x16x32_bf16 v[220:223], v[236:239], v[118:121], v[220:223]
	ds_read_b128 v[236:239], v186 offset:61440
	v_add_f32_e32 v133, v89, v133
	v_add_f32_e32 v132, v90, v132
	v_add_f32_e32 v133, v91, v133
	s_waitcnt lgkmcnt(7)
	v_mfma_f32_16x16x32_bf16 v[192:195], v[166:169], v[106:109], v[192:195]
	v_mfma_f32_16x16x32_bf16 v[208:211], v[166:169], v[122:125], v[208:211]
	ds_read_b64_tr_b16 v[166:167], v240 offset:0
	ds_read_b64_tr_b16 v[168:169], v240 offset:4096
	v_add_f32_e32 v132, v92, v132
	v_add_f32_e32 v133, v93, v133
	v_add_f32_e32 v132, v94, v132
	s_waitcnt lgkmcnt(8)
	v_mfma_f32_16x16x32_bf16 v[196:199], v[170:173], v[106:109], v[196:199]
	v_mfma_f32_16x16x32_bf16 v[212:215], v[170:173], v[122:125], v[212:215]
	ds_read_b64_tr_b16 v[170:171], v241 offset:0
	ds_read_b64_tr_b16 v[172:173], v241 offset:4096
	v_add_f32_e32 v133, v95, v133
	v_add_f32_e32 v132, v96, v132
	v_add_f32_e32 v133, v97, v133
	s_waitcnt lgkmcnt(9)
	v_mfma_f32_16x16x32_bf16 v[200:203], v[174:177], v[106:109], v[200:203]
	v_mfma_f32_16x16x32_bf16 v[216:219], v[174:177], v[122:125], v[216:219]
	ds_read_b64_tr_b16 v[174:175], v242 offset:0
	ds_read_b64_tr_b16 v[176:177], v242 offset:4096
	v_add_f32_e32 v132, v132, v133
	v_add_f32_e32 v163, v163, v132
	v_cvt_pk_bf16_f32 v66, v66, v67
	s_waitcnt lgkmcnt(10)
	v_mfma_f32_16x16x32_bf16 v[204:207], v[178:181], v[106:109], v[204:207]
	v_mfma_f32_16x16x32_bf16 v[220:223], v[178:181], v[122:125], v[220:223]
	ds_read_b64_tr_b16 v[178:179], v243 offset:0
	ds_read_b64_tr_b16 v[180:181], v243 offset:4096
	v_cvt_pk_bf16_f32 v67, v68, v69
	v_cvt_pk_bf16_f32 v68, v70, v71
	v_cvt_pk_bf16_f32 v69, v72, v73
	s_waitcnt lgkmcnt(11)
	v_mfma_f32_16x16x32_bf16 v[192:195], v[224:227], v[110:113], v[192:195]
	v_mfma_f32_16x16x32_bf16 v[208:211], v[224:227], v[126:129], v[208:211]
	ds_read_b64_tr_b16 v[224:225], v244 offset:0
	ds_read_b64_tr_b16 v[226:227], v244 offset:4096
	v_cvt_pk_bf16_f32 v74, v74, v75
	v_cvt_pk_bf16_f32 v75, v76, v77
	v_cvt_pk_bf16_f32 v76, v78, v79
	s_waitcnt lgkmcnt(12)
	v_mfma_f32_16x16x32_bf16 v[196:199], v[228:231], v[110:113], v[196:199]
	v_mfma_f32_16x16x32_bf16 v[212:215], v[228:231], v[126:129], v[212:215]
	ds_read_b64_tr_b16 v[228:229], v245 offset:0
	ds_read_b64_tr_b16 v[230:231], v245 offset:4096
	v_cvt_pk_bf16_f32 v77, v80, v81
	v_cvt_pk_bf16_f32 v82, v82, v83
	v_cvt_pk_bf16_f32 v83, v84, v85
	s_waitcnt lgkmcnt(13)
	v_mfma_f32_16x16x32_bf16 v[200:203], v[232:235], v[110:113], v[200:203]
	v_mfma_f32_16x16x32_bf16 v[216:219], v[232:235], v[126:129], v[216:219]
	v_cvt_pk_bf16_f32 v84, v86, v87
	v_cvt_pk_bf16_f32 v85, v88, v89
	v_cvt_pk_bf16_f32 v90, v90, v91
	s_waitcnt lgkmcnt(12)
	v_mfma_f32_16x16x32_bf16 v[204:207], v[236:239], v[110:113], v[204:207]
	v_mfma_f32_16x16x32_bf16 v[220:223], v[236:239], v[126:129], v[220:223]
	v_cvt_pk_bf16_f32 v91, v92, v93
	v_cvt_pk_bf16_f32 v92, v94, v95
	v_cvt_pk_bf16_f32 v93, v96, v97
	s_waitcnt lgkmcnt(10)
	v_mfma_f32_16x16x32_bf16 v[2:5], v[66:69], v[166:169], v[2:5]
	v_mfma_f32_16x16x32_bf16 v[34:37], v[82:85], v[166:169], v[34:37]
	ds_read_b64_tr_b16 v[232:233], v246 offset:0
	ds_read_b64_tr_b16 v[234:235], v246 offset:4096
	s_waitcnt lgkmcnt(10)
	v_mfma_f32_16x16x32_bf16 v[6:9], v[66:69], v[170:173], v[6:9]
	v_mfma_f32_16x16x32_bf16 v[38:41], v[82:85], v[170:173], v[38:41]
	ds_read_b64_tr_b16 v[236:237], v247 offset:0
	ds_read_b64_tr_b16 v[238:239], v247 offset:4096
	s_waitcnt lgkmcnt(10)
	v_mfma_f32_16x16x32_bf16 v[10:13], v[66:69], v[174:177], v[10:13]
	v_mfma_f32_16x16x32_bf16 v[42:45], v[82:85], v[174:177], v[42:45]
	ds_read_b64_tr_b16 v[166:167], v240 offset:8192
	ds_read_b64_tr_b16 v[168:169], v240 offset:12288
	v_exp_f32_e32 v192, v192
	v_exp_f32_e32 v193, v193
	v_exp_f32_e32 v194, v194
	s_waitcnt lgkmcnt(10)
	v_mfma_f32_16x16x32_bf16 v[14:17], v[66:69], v[178:181], v[14:17]
	v_mfma_f32_16x16x32_bf16 v[46:49], v[82:85], v[178:181], v[46:49]
	ds_read_b64_tr_b16 v[170:171], v241 offset:8192
	ds_read_b64_tr_b16 v[172:173], v241 offset:12288
	v_exp_f32_e32 v195, v195
	v_exp_f32_e32 v208, v208
	s_waitcnt lgkmcnt(10)
	v_mfma_f32_16x16x32_bf16 v[18:21], v[66:69], v[224:227], v[18:21]
	v_mfma_f32_16x16x32_bf16 v[50:53], v[82:85], v[224:227], v[50:53]
	ds_read_b64_tr_b16 v[174:175], v242 offset:8192
	ds_read_b64_tr_b16 v[176:177], v242 offset:12288
	v_exp_f32_e32 v209, v209
	v_exp_f32_e32 v210, v210
	s_waitcnt lgkmcnt(10)
	v_mfma_f32_16x16x32_bf16 v[22:25], v[66:69], v[228:231], v[22:25]
	v_mfma_f32_16x16x32_bf16 v[54:57], v[82:85], v[228:231], v[54:57]
	ds_read_b64_tr_b16 v[178:179], v243 offset:8192
	ds_read_b64_tr_b16 v[180:181], v243 offset:12288
	v_exp_f32_e32 v211, v211
	v_exp_f32_e32 v196, v196
	v_exp_f32_e32 v197, v197
	s_waitcnt lgkmcnt(10)
	v_mfma_f32_16x16x32_bf16 v[26:29], v[66:69], v[232:235], v[26:29]
	v_mfma_f32_16x16x32_bf16 v[58:61], v[82:85], v[232:235], v[58:61]
	ds_read_b64_tr_b16 v[224:225], v244 offset:8192
	ds_read_b64_tr_b16 v[226:227], v244 offset:12288
	v_exp_f32_e32 v198, v198
	v_exp_f32_e32 v199, v199
	s_waitcnt lgkmcnt(10)
	v_mfma_f32_16x16x32_bf16 v[30:33], v[66:69], v[236:239], v[30:33]
	v_mfma_f32_16x16x32_bf16 v[62:65], v[82:85], v[236:239], v[62:65]
	ds_read_b64_tr_b16 v[228:229], v245 offset:8192
	ds_read_b64_tr_b16 v[230:231], v245 offset:12288
	v_exp_f32_e32 v212, v212
	v_exp_f32_e32 v213, v213
	s_waitcnt lgkmcnt(10)
	v_mfma_f32_16x16x32_bf16 v[2:5], v[74:77], v[166:169], v[2:5]
	v_mfma_f32_16x16x32_bf16 v[34:37], v[90:93], v[166:169], v[34:37]
	ds_read_b64_tr_b16 v[232:233], v246 offset:8192
	ds_read_b64_tr_b16 v[234:235], v246 offset:12288
	ds_read_b128 v[166:169], v187 offset:16384
	v_exp_f32_e32 v214, v214
	v_exp_f32_e32 v215, v215
	s_waitcnt lgkmcnt(11)
	v_mfma_f32_16x16x32_bf16 v[6:9], v[74:77], v[170:173], v[6:9]
	v_mfma_f32_16x16x32_bf16 v[38:41], v[90:93], v[170:173], v[38:41]
	ds_read_b64_tr_b16 v[236:237], v247 offset:8192
	ds_read_b64_tr_b16 v[238:239], v247 offset:12288
	ds_read_b128 v[170:173], v187 offset:20480
	v_exp_f32_e32 v200, v200
	v_exp_f32_e32 v201, v201
	v_exp_f32_e32 v202, v202
	s_waitcnt lgkmcnt(12)
	v_mfma_f32_16x16x32_bf16 v[10:13], v[74:77], v[174:177], v[10:13]
	v_mfma_f32_16x16x32_bf16 v[42:45], v[90:93], v[174:177], v[42:45]
	ds_read_b128 v[174:177], v187 offset:24576
	v_exp_f32_e32 v203, v203
	v_exp_f32_e32 v216, v216
	s_waitcnt lgkmcnt(11)
	v_mfma_f32_16x16x32_bf16 v[14:17], v[74:77], v[178:181], v[14:17]
	v_mfma_f32_16x16x32_bf16 v[46:49], v[90:93], v[178:181], v[46:49]
	ds_read_b128 v[178:181], v187 offset:28672
	v_exp_f32_e32 v217, v217
	v_exp_f32_e32 v218, v218
	s_waitcnt lgkmcnt(10)
	v_mfma_f32_16x16x32_bf16 v[18:21], v[74:77], v[224:227], v[18:21]
	v_mfma_f32_16x16x32_bf16 v[50:53], v[90:93], v[224:227], v[50:53]
	ds_read_b128 v[224:227], v188 offset:16384
	v_exp_f32_e32 v219, v219
	v_exp_f32_e32 v204, v204
	v_exp_f32_e32 v205, v205
	s_waitcnt lgkmcnt(9)
	v_mfma_f32_16x16x32_bf16 v[22:25], v[74:77], v[228:231], v[22:25]
	v_mfma_f32_16x16x32_bf16 v[54:57], v[90:93], v[228:231], v[54:57]
	ds_read_b128 v[228:231], v188 offset:20480
	v_exp_f32_e32 v206, v206
	v_exp_f32_e32 v207, v207
	s_waitcnt lgkmcnt(8)
	v_mfma_f32_16x16x32_bf16 v[26:29], v[74:77], v[232:235], v[26:29]
	v_mfma_f32_16x16x32_bf16 v[58:61], v[90:93], v[232:235], v[58:61]
	ds_read_b128 v[232:235], v188 offset:24576
	v_exp_f32_e32 v220, v220
	v_exp_f32_e32 v221, v221
	s_waitcnt lgkmcnt(6)
	v_mfma_f32_16x16x32_bf16 v[30:33], v[74:77], v[236:239], v[30:33]
	v_mfma_f32_16x16x32_bf16 v[62:65], v[90:93], v[236:239], v[62:65]
	ds_read_b128 v[236:239], v188 offset:28672
	v_exp_f32_e32 v222, v222
	v_exp_f32_e32 v223, v223
	s_waitcnt vmcnt(0)
	s_barrier
	v_mfma_f32_16x16x32_bf16 v[66:69], v[166:169], v[98:101], 0
	v_mfma_f32_16x16x32_bf16 v[82:85], v[166:169], v[114:117], 0
	ds_read_b128 v[166:169], v189 offset:16384
	v_add_f32_e32 v130, v192, v193
	v_add_f32_e32 v131, v194, v195
	v_add_f32_e32 v130, v196, v130
	s_waitcnt lgkmcnt(7)
	v_mfma_f32_16x16x32_bf16 v[70:73], v[170:173], v[98:101], 0
	v_mfma_f32_16x16x32_bf16 v[86:89], v[170:173], v[114:117], 0
	ds_read_b128 v[170:173], v189 offset:20480
	v_add_f32_e32 v131, v197, v131
	v_add_f32_e32 v130, v198, v130
	v_add_f32_e32 v131, v199, v131
	s_waitcnt lgkmcnt(7)
	v_mfma_f32_16x16x32_bf16 v[74:77], v[174:177], v[98:101], 0
	v_mfma_f32_16x16x32_bf16 v[90:93], v[174:177], v[114:117], 0
	ds_read_b128 v[174:177], v189 offset:24576
	v_add_f32_e32 v130, v200, v130
	v_add_f32_e32 v131, v201, v131
	v_add_f32_e32 v130, v202, v130
	s_waitcnt lgkmcnt(7)
	v_mfma_f32_16x16x32_bf16 v[78:81], v[178:181], v[98:101], 0
	v_mfma_f32_16x16x32_bf16 v[94:97], v[178:181], v[114:117], 0
	ds_read_b128 v[178:181], v189 offset:28672
	v_add_f32_e32 v131, v203, v131
	v_add_f32_e32 v130, v204, v130
	v_add_f32_e32 v131, v205, v131
	s_waitcnt lgkmcnt(7)
	v_mfma_f32_16x16x32_bf16 v[66:69], v[224:227], v[102:105], v[66:69]
	v_mfma_f32_16x16x32_bf16 v[82:85], v[224:227], v[118:121], v[82:85]
	ds_read_b128 v[224:227], v190 offset:16384
	v_add_f32_e32 v130, v206, v130
	v_add_f32_e32 v131, v207, v131
	v_add_f32_e32 v130, v130, v131
	s_waitcnt lgkmcnt(7)
	v_mfma_f32_16x16x32_bf16 v[70:73], v[228:231], v[102:105], v[70:73]
	v_mfma_f32_16x16x32_bf16 v[86:89], v[228:231], v[118:121], v[86:89]
	ds_read_b128 v[228:231], v190 offset:20480
	v_add_f32_e32 v165, v165, v130
	v_add_f32_e32 v132, v208, v209
	v_add_f32_e32 v133, v210, v211
	s_waitcnt lgkmcnt(7)
	v_mfma_f32_16x16x32_bf16 v[74:77], v[232:235], v[102:105], v[74:77]
	v_mfma_f32_16x16x32_bf16 v[90:93], v[232:235], v[118:121], v[90:93]
	ds_read_b128 v[232:235], v190 offset:24576
	v_add_f32_e32 v132, v212, v132
	v_add_f32_e32 v133, v213, v133
	v_add_f32_e32 v132, v214, v132
	s_waitcnt lgkmcnt(7)
	v_mfma_f32_16x16x32_bf16 v[78:81], v[236:239], v[102:105], v[78:81]
	v_mfma_f32_16x16x32_bf16 v[94:97], v[236:239], v[118:121], v[94:97]
	ds_read_b128 v[236:239], v190 offset:28672
	v_add_f32_e32 v133, v215, v133
	v_add_f32_e32 v132, v216, v132
	v_add_f32_e32 v133, v217, v133
	s_waitcnt lgkmcnt(7)
	v_mfma_f32_16x16x32_bf16 v[66:69], v[166:169], v[106:109], v[66:69]
	v_mfma_f32_16x16x32_bf16 v[82:85], v[166:169], v[122:125], v[82:85]
	ds_read_b64_tr_b16 v[166:167], v240 offset:32768
	ds_read_b64_tr_b16 v[168:169], v240 offset:36864
	v_add_f32_e32 v132, v218, v132
	v_add_f32_e32 v133, v219, v133
	v_add_f32_e32 v132, v220, v132
	s_waitcnt lgkmcnt(8)
	v_mfma_f32_16x16x32_bf16 v[70:73], v[170:173], v[106:109], v[70:73]
	v_mfma_f32_16x16x32_bf16 v[86:89], v[170:173], v[122:125], v[86:89]
	ds_read_b64_tr_b16 v[170:171], v241 offset:32768
	ds_read_b64_tr_b16 v[172:173], v241 offset:36864
	v_add_f32_e32 v133, v221, v133
	v_add_f32_e32 v132, v222, v132
	v_add_f32_e32 v133, v223, v133
	s_waitcnt lgkmcnt(9)
	v_mfma_f32_16x16x32_bf16 v[74:77], v[174:177], v[106:109], v[74:77]
	v_mfma_f32_16x16x32_bf16 v[90:93], v[174:177], v[122:125], v[90:93]
	ds_read_b64_tr_b16 v[174:175], v242 offset:32768
	ds_read_b64_tr_b16 v[176:177], v242 offset:36864
	v_add_f32_e32 v132, v132, v133
	v_add_f32_e32 v163, v163, v132
	v_cvt_pk_bf16_f32 v192, v192, v193
	s_waitcnt lgkmcnt(10)
	v_mfma_f32_16x16x32_bf16 v[78:81], v[178:181], v[106:109], v[78:81]
	v_mfma_f32_16x16x32_bf16 v[94:97], v[178:181], v[122:125], v[94:97]
	ds_read_b64_tr_b16 v[178:179], v243 offset:32768
	ds_read_b64_tr_b16 v[180:181], v243 offset:36864
	v_cvt_pk_bf16_f32 v193, v194, v195
	v_cvt_pk_bf16_f32 v194, v196, v197
	v_cvt_pk_bf16_f32 v195, v198, v199
	s_waitcnt lgkmcnt(11)
	v_mfma_f32_16x16x32_bf16 v[66:69], v[224:227], v[110:113], v[66:69]
	v_mfma_f32_16x16x32_bf16 v[82:85], v[224:227], v[126:129], v[82:85]
	ds_read_b64_tr_b16 v[224:225], v244 offset:32768
	ds_read_b64_tr_b16 v[226:227], v244 offset:36864
	v_cvt_pk_bf16_f32 v200, v200, v201
	v_cvt_pk_bf16_f32 v201, v202, v203
	v_cvt_pk_bf16_f32 v202, v204, v205
	s_waitcnt lgkmcnt(12)
	v_mfma_f32_16x16x32_bf16 v[70:73], v[228:231], v[110:113], v[70:73]
	v_mfma_f32_16x16x32_bf16 v[86:89], v[228:231], v[126:129], v[86:89]
	ds_read_b64_tr_b16 v[228:229], v245 offset:32768
	ds_read_b64_tr_b16 v[230:231], v245 offset:36864
	v_cvt_pk_bf16_f32 v203, v206, v207
	v_cvt_pk_bf16_f32 v208, v208, v209
	v_cvt_pk_bf16_f32 v209, v210, v211
	s_waitcnt lgkmcnt(13)
	v_mfma_f32_16x16x32_bf16 v[74:77], v[232:235], v[110:113], v[74:77]
	v_mfma_f32_16x16x32_bf16 v[90:93], v[232:235], v[126:129], v[90:93]
	v_cvt_pk_bf16_f32 v210, v212, v213
	v_cvt_pk_bf16_f32 v211, v214, v215
	v_cvt_pk_bf16_f32 v216, v216, v217
	s_waitcnt lgkmcnt(12)
	v_mfma_f32_16x16x32_bf16 v[78:81], v[236:239], v[110:113], v[78:81]
	v_mfma_f32_16x16x32_bf16 v[94:97], v[236:239], v[126:129], v[94:97]
	v_cvt_pk_bf16_f32 v217, v218, v219
	v_cvt_pk_bf16_f32 v218, v220, v221
	v_cvt_pk_bf16_f32 v219, v222, v223
	s_waitcnt lgkmcnt(10)
	v_mfma_f32_16x16x32_bf16 v[2:5], v[192:195], v[166:169], v[2:5]
	v_mfma_f32_16x16x32_bf16 v[34:37], v[208:211], v[166:169], v[34:37]
	ds_read_b64_tr_b16 v[232:233], v246 offset:32768
	ds_read_b64_tr_b16 v[234:235], v246 offset:36864
	s_waitcnt lgkmcnt(10)
	v_mfma_f32_16x16x32_bf16 v[6:9], v[192:195], v[170:173], v[6:9]
	v_mfma_f32_16x16x32_bf16 v[38:41], v[208:211], v[170:173], v[38:41]
	ds_read_b64_tr_b16 v[236:237], v247 offset:32768
	ds_read_b64_tr_b16 v[238:239], v247 offset:36864
	s_waitcnt lgkmcnt(10)
	v_mfma_f32_16x16x32_bf16 v[10:13], v[192:195], v[174:177], v[10:13]
	v_mfma_f32_16x16x32_bf16 v[42:45], v[208:211], v[174:177], v[42:45]
	ds_read_b64_tr_b16 v[166:167], v240 offset:40960
	ds_read_b64_tr_b16 v[168:169], v240 offset:45056
	v_exp_f32_e32 v66, v66
	v_exp_f32_e32 v67, v67
	v_exp_f32_e32 v68, v68
	s_waitcnt lgkmcnt(10)
	v_mfma_f32_16x16x32_bf16 v[14:17], v[192:195], v[178:181], v[14:17]
	v_mfma_f32_16x16x32_bf16 v[46:49], v[208:211], v[178:181], v[46:49]
	ds_read_b64_tr_b16 v[170:171], v241 offset:40960
	ds_read_b64_tr_b16 v[172:173], v241 offset:45056
	v_exp_f32_e32 v69, v69
	v_exp_f32_e32 v82, v82
	s_waitcnt lgkmcnt(10)
	v_mfma_f32_16x16x32_bf16 v[18:21], v[192:195], v[224:227], v[18:21]
	v_mfma_f32_16x16x32_bf16 v[50:53], v[208:211], v[224:227], v[50:53]
	ds_read_b64_tr_b16 v[174:175], v242 offset:40960
	ds_read_b64_tr_b16 v[176:177], v242 offset:45056
	v_exp_f32_e32 v83, v83
	v_exp_f32_e32 v84, v84
	s_waitcnt lgkmcnt(10)
	v_mfma_f32_16x16x32_bf16 v[22:25], v[192:195], v[228:231], v[22:25]
	v_mfma_f32_16x16x32_bf16 v[54:57], v[208:211], v[228:231], v[54:57]
	ds_read_b64_tr_b16 v[178:179], v243 offset:40960
	ds_read_b64_tr_b16 v[180:181], v243 offset:45056
	v_exp_f32_e32 v85, v85
	v_exp_f32_e32 v70, v70
	v_exp_f32_e32 v71, v71
	s_waitcnt lgkmcnt(10)
	v_mfma_f32_16x16x32_bf16 v[26:29], v[192:195], v[232:235], v[26:29]
	v_mfma_f32_16x16x32_bf16 v[58:61], v[208:211], v[232:235], v[58:61]
	ds_read_b64_tr_b16 v[224:225], v244 offset:40960
	ds_read_b64_tr_b16 v[226:227], v244 offset:45056
	v_exp_f32_e32 v72, v72
	v_exp_f32_e32 v73, v73
	s_waitcnt lgkmcnt(10)
	v_mfma_f32_16x16x32_bf16 v[30:33], v[192:195], v[236:239], v[30:33]
	v_mfma_f32_16x16x32_bf16 v[62:65], v[208:211], v[236:239], v[62:65]
	ds_read_b64_tr_b16 v[228:229], v245 offset:40960
	ds_read_b64_tr_b16 v[230:231], v245 offset:45056
	v_exp_f32_e32 v86, v86
	v_exp_f32_e32 v87, v87
	s_waitcnt lgkmcnt(10)
	v_mfma_f32_16x16x32_bf16 v[2:5], v[200:203], v[166:169], v[2:5]
	v_mfma_f32_16x16x32_bf16 v[34:37], v[216:219], v[166:169], v[34:37]
	ds_read_b64_tr_b16 v[232:233], v246 offset:40960
	ds_read_b64_tr_b16 v[234:235], v246 offset:45056
	ds_read_b128 v[166:169], v187 offset:49152
	v_exp_f32_e32 v88, v88
	v_exp_f32_e32 v89, v89
	s_waitcnt lgkmcnt(11)
	v_mfma_f32_16x16x32_bf16 v[6:9], v[200:203], v[170:173], v[6:9]
	v_mfma_f32_16x16x32_bf16 v[38:41], v[216:219], v[170:173], v[38:41]
	ds_read_b64_tr_b16 v[236:237], v247 offset:40960
	ds_read_b64_tr_b16 v[238:239], v247 offset:45056
	ds_read_b128 v[170:173], v187 offset:53248
	v_exp_f32_e32 v74, v74
	v_exp_f32_e32 v75, v75
	v_exp_f32_e32 v76, v76
	s_waitcnt lgkmcnt(12)
	v_mfma_f32_16x16x32_bf16 v[10:13], v[200:203], v[174:177], v[10:13]
	v_mfma_f32_16x16x32_bf16 v[42:45], v[216:219], v[174:177], v[42:45]
	ds_read_b128 v[174:177], v187 offset:57344
	v_exp_f32_e32 v77, v77
	v_exp_f32_e32 v90, v90
	s_waitcnt lgkmcnt(11)
	v_mfma_f32_16x16x32_bf16 v[14:17], v[200:203], v[178:181], v[14:17]
	v_mfma_f32_16x16x32_bf16 v[46:49], v[216:219], v[178:181], v[46:49]
	ds_read_b128 v[178:181], v187 offset:61440
	v_exp_f32_e32 v91, v91
	v_exp_f32_e32 v92, v92
	s_waitcnt lgkmcnt(10)
	v_mfma_f32_16x16x32_bf16 v[18:21], v[200:203], v[224:227], v[18:21]
	v_mfma_f32_16x16x32_bf16 v[50:53], v[216:219], v[224:227], v[50:53]
	ds_read_b128 v[224:227], v188 offset:49152
	v_exp_f32_e32 v93, v93
	v_exp_f32_e32 v78, v78
	v_exp_f32_e32 v79, v79
	s_waitcnt lgkmcnt(9)
	v_mfma_f32_16x16x32_bf16 v[22:25], v[200:203], v[228:231], v[22:25]
	v_mfma_f32_16x16x32_bf16 v[54:57], v[216:219], v[228:231], v[54:57]
	ds_read_b128 v[228:231], v188 offset:53248
	v_exp_f32_e32 v80, v80
	v_exp_f32_e32 v81, v81
	s_waitcnt lgkmcnt(8)
	v_mfma_f32_16x16x32_bf16 v[26:29], v[200:203], v[232:235], v[26:29]
	v_mfma_f32_16x16x32_bf16 v[58:61], v[216:219], v[232:235], v[58:61]
	ds_read_b128 v[232:235], v188 offset:57344
	v_exp_f32_e32 v94, v94
	v_exp_f32_e32 v95, v95
	s_waitcnt lgkmcnt(6)
	v_mfma_f32_16x16x32_bf16 v[30:33], v[200:203], v[236:239], v[30:33]
	v_mfma_f32_16x16x32_bf16 v[62:65], v[216:219], v[236:239], v[62:65]
	ds_read_b128 v[236:239], v188 offset:61440
	v_exp_f32_e32 v96, v96
	v_exp_f32_e32 v97, v97
	s_waitcnt vmcnt(0)
	s_barrier
	v_mfma_f32_16x16x32_bf16 v[192:195], v[166:169], v[98:101], 0
	v_mfma_f32_16x16x32_bf16 v[208:211], v[166:169], v[114:117], 0
	ds_read_b128 v[166:169], v189 offset:49152
	v_add_f32_e32 v130, v66, v67
	v_add_f32_e32 v131, v68, v69
	v_add_f32_e32 v130, v70, v130
	s_waitcnt lgkmcnt(7)
	v_mfma_f32_16x16x32_bf16 v[196:199], v[170:173], v[98:101], 0
	v_mfma_f32_16x16x32_bf16 v[212:215], v[170:173], v[114:117], 0
	ds_read_b128 v[170:173], v189 offset:53248
	v_add_f32_e32 v131, v71, v131
	v_add_f32_e32 v130, v72, v130
	v_add_f32_e32 v131, v73, v131
	s_waitcnt lgkmcnt(7)
	v_mfma_f32_16x16x32_bf16 v[200:203], v[174:177], v[98:101], 0
	v_mfma_f32_16x16x32_bf16 v[216:219], v[174:177], v[114:117], 0
	ds_read_b128 v[174:177], v189 offset:57344
	v_add_f32_e32 v130, v74, v130
	v_add_f32_e32 v131, v75, v131
	v_add_f32_e32 v130, v76, v130
	s_waitcnt lgkmcnt(7)
	v_mfma_f32_16x16x32_bf16 v[204:207], v[178:181], v[98:101], 0
	v_mfma_f32_16x16x32_bf16 v[220:223], v[178:181], v[114:117], 0
	ds_read_b128 v[178:181], v189 offset:61440
	v_add_f32_e32 v131, v77, v131
	v_add_f32_e32 v130, v78, v130
	v_add_f32_e32 v131, v79, v131
	s_waitcnt lgkmcnt(7)
	v_mfma_f32_16x16x32_bf16 v[192:195], v[224:227], v[102:105], v[192:195]
	v_mfma_f32_16x16x32_bf16 v[208:211], v[224:227], v[118:121], v[208:211]
	ds_read_b128 v[224:227], v190 offset:49152
	v_add_f32_e32 v130, v80, v130
	v_add_f32_e32 v131, v81, v131
	v_add_f32_e32 v130, v130, v131
	s_waitcnt lgkmcnt(7)
	v_mfma_f32_16x16x32_bf16 v[196:199], v[228:231], v[102:105], v[196:199]
	v_mfma_f32_16x16x32_bf16 v[212:215], v[228:231], v[118:121], v[212:215]
	ds_read_b128 v[228:231], v190 offset:53248
	v_add_f32_e32 v165, v165, v130
	v_add_f32_e32 v132, v82, v83
	v_add_f32_e32 v133, v84, v85
	s_waitcnt lgkmcnt(7)
	v_mfma_f32_16x16x32_bf16 v[200:203], v[232:235], v[102:105], v[200:203]
	v_mfma_f32_16x16x32_bf16 v[216:219], v[232:235], v[118:121], v[216:219]
	ds_read_b128 v[232:235], v190 offset:57344
	v_add_f32_e32 v132, v86, v132
	v_add_f32_e32 v133, v87, v133
	v_add_f32_e32 v132, v88, v132
	s_waitcnt lgkmcnt(7)
	v_mfma_f32_16x16x32_bf16 v[204:207], v[236:239], v[102:105], v[204:207]
	v_mfma_f32_16x16x32_bf16 v[220:223], v[236:239], v[118:121], v[220:223]
	ds_read_b128 v[236:239], v190 offset:61440
	v_add_f32_e32 v133, v89, v133
	v_add_f32_e32 v132, v90, v132
	v_add_f32_e32 v133, v91, v133
	s_waitcnt lgkmcnt(7)
	v_mfma_f32_16x16x32_bf16 v[192:195], v[166:169], v[106:109], v[192:195]
	v_mfma_f32_16x16x32_bf16 v[208:211], v[166:169], v[122:125], v[208:211]
	ds_read_b64_tr_b16 v[166:167], v142 offset:0
	ds_read_b64_tr_b16 v[168:169], v142 offset:4096
	v_add_f32_e32 v132, v92, v132
	v_add_f32_e32 v133, v93, v133
	v_add_f32_e32 v132, v94, v132
	s_waitcnt lgkmcnt(8)
	v_mfma_f32_16x16x32_bf16 v[196:199], v[170:173], v[106:109], v[196:199]
	v_mfma_f32_16x16x32_bf16 v[212:215], v[170:173], v[122:125], v[212:215]
	ds_read_b64_tr_b16 v[170:171], v143 offset:0
	ds_read_b64_tr_b16 v[172:173], v143 offset:4096
	v_add_f32_e32 v133, v95, v133
	v_add_f32_e32 v132, v96, v132
	v_add_f32_e32 v133, v97, v133
	s_waitcnt lgkmcnt(9)
	v_mfma_f32_16x16x32_bf16 v[200:203], v[174:177], v[106:109], v[200:203]
	v_mfma_f32_16x16x32_bf16 v[216:219], v[174:177], v[122:125], v[216:219]
	ds_read_b64_tr_b16 v[174:175], v144 offset:0
	ds_read_b64_tr_b16 v[176:177], v144 offset:4096
	v_add_f32_e32 v132, v132, v133
	v_add_f32_e32 v163, v163, v132
	v_cvt_pk_bf16_f32 v66, v66, v67
	s_waitcnt lgkmcnt(10)
	v_mfma_f32_16x16x32_bf16 v[204:207], v[178:181], v[106:109], v[204:207]
	v_mfma_f32_16x16x32_bf16 v[220:223], v[178:181], v[122:125], v[220:223]
	ds_read_b64_tr_b16 v[178:179], v145 offset:0
	ds_read_b64_tr_b16 v[180:181], v145 offset:4096
	v_cvt_pk_bf16_f32 v67, v68, v69
	v_cvt_pk_bf16_f32 v68, v70, v71
	v_cvt_pk_bf16_f32 v69, v72, v73
	s_waitcnt lgkmcnt(11)
	v_mfma_f32_16x16x32_bf16 v[192:195], v[224:227], v[110:113], v[192:195]
	v_mfma_f32_16x16x32_bf16 v[208:211], v[224:227], v[126:129], v[208:211]
	ds_read_b64_tr_b16 v[224:225], v146 offset:0
	ds_read_b64_tr_b16 v[226:227], v146 offset:4096
	v_cvt_pk_bf16_f32 v74, v74, v75
	v_cvt_pk_bf16_f32 v75, v76, v77
	v_cvt_pk_bf16_f32 v76, v78, v79
	s_waitcnt lgkmcnt(12)
	v_mfma_f32_16x16x32_bf16 v[196:199], v[228:231], v[110:113], v[196:199]
	v_mfma_f32_16x16x32_bf16 v[212:215], v[228:231], v[126:129], v[212:215]
	ds_read_b64_tr_b16 v[228:229], v147 offset:0
	ds_read_b64_tr_b16 v[230:231], v147 offset:4096
	v_cvt_pk_bf16_f32 v77, v80, v81
	v_cvt_pk_bf16_f32 v82, v82, v83
	v_cvt_pk_bf16_f32 v83, v84, v85
	s_waitcnt lgkmcnt(13)
	v_mfma_f32_16x16x32_bf16 v[200:203], v[232:235], v[110:113], v[200:203]
	v_mfma_f32_16x16x32_bf16 v[216:219], v[232:235], v[126:129], v[216:219]
	v_cvt_pk_bf16_f32 v84, v86, v87
	v_cvt_pk_bf16_f32 v85, v88, v89
	v_cvt_pk_bf16_f32 v90, v90, v91
	s_waitcnt lgkmcnt(12)
	v_mfma_f32_16x16x32_bf16 v[204:207], v[236:239], v[110:113], v[204:207]
	v_mfma_f32_16x16x32_bf16 v[220:223], v[236:239], v[126:129], v[220:223]
	v_cvt_pk_bf16_f32 v91, v92, v93
	v_cvt_pk_bf16_f32 v92, v94, v95
	v_cvt_pk_bf16_f32 v93, v96, v97
	s_waitcnt lgkmcnt(10)
	v_mfma_f32_16x16x32_bf16 v[2:5], v[66:69], v[166:169], v[2:5]
	v_mfma_f32_16x16x32_bf16 v[34:37], v[82:85], v[166:169], v[34:37]
	ds_read_b64_tr_b16 v[232:233], v148 offset:0
	ds_read_b64_tr_b16 v[234:235], v148 offset:4096
	s_waitcnt lgkmcnt(10)
	v_mfma_f32_16x16x32_bf16 v[6:9], v[66:69], v[170:173], v[6:9]
	v_mfma_f32_16x16x32_bf16 v[38:41], v[82:85], v[170:173], v[38:41]
	ds_read_b64_tr_b16 v[236:237], v149 offset:0
	ds_read_b64_tr_b16 v[238:239], v149 offset:4096
	s_waitcnt lgkmcnt(10)
	v_mfma_f32_16x16x32_bf16 v[10:13], v[66:69], v[174:177], v[10:13]
	v_mfma_f32_16x16x32_bf16 v[42:45], v[82:85], v[174:177], v[42:45]
	ds_read_b64_tr_b16 v[166:167], v142 offset:8192
	ds_read_b64_tr_b16 v[168:169], v142 offset:12288
	v_exp_f32_e32 v192, v192
	v_exp_f32_e32 v193, v193
	v_exp_f32_e32 v194, v194
	s_waitcnt lgkmcnt(10)
	v_mfma_f32_16x16x32_bf16 v[14:17], v[66:69], v[178:181], v[14:17]
	v_mfma_f32_16x16x32_bf16 v[46:49], v[82:85], v[178:181], v[46:49]
	ds_read_b64_tr_b16 v[170:171], v143 offset:8192
	ds_read_b64_tr_b16 v[172:173], v143 offset:12288
	v_exp_f32_e32 v195, v195
	v_exp_f32_e32 v208, v208
	s_waitcnt lgkmcnt(10)
	v_mfma_f32_16x16x32_bf16 v[18:21], v[66:69], v[224:227], v[18:21]
	v_mfma_f32_16x16x32_bf16 v[50:53], v[82:85], v[224:227], v[50:53]
	ds_read_b64_tr_b16 v[174:175], v144 offset:8192
	ds_read_b64_tr_b16 v[176:177], v144 offset:12288
	v_exp_f32_e32 v209, v209
	v_exp_f32_e32 v210, v210
	s_waitcnt lgkmcnt(10)
	v_mfma_f32_16x16x32_bf16 v[22:25], v[66:69], v[228:231], v[22:25]
	v_mfma_f32_16x16x32_bf16 v[54:57], v[82:85], v[228:231], v[54:57]
	ds_read_b64_tr_b16 v[178:179], v145 offset:8192
	ds_read_b64_tr_b16 v[180:181], v145 offset:12288
	v_exp_f32_e32 v211, v211
	v_exp_f32_e32 v196, v196
	v_exp_f32_e32 v197, v197
	s_waitcnt lgkmcnt(10)
	v_mfma_f32_16x16x32_bf16 v[26:29], v[66:69], v[232:235], v[26:29]
	v_mfma_f32_16x16x32_bf16 v[58:61], v[82:85], v[232:235], v[58:61]
	ds_read_b64_tr_b16 v[224:225], v146 offset:8192
	ds_read_b64_tr_b16 v[226:227], v146 offset:12288
	v_exp_f32_e32 v198, v198
	v_exp_f32_e32 v199, v199
	s_waitcnt lgkmcnt(10)
	v_mfma_f32_16x16x32_bf16 v[30:33], v[66:69], v[236:239], v[30:33]
	v_mfma_f32_16x16x32_bf16 v[62:65], v[82:85], v[236:239], v[62:65]
	ds_read_b64_tr_b16 v[228:229], v147 offset:8192
	ds_read_b64_tr_b16 v[230:231], v147 offset:12288
	v_exp_f32_e32 v212, v212
	v_exp_f32_e32 v213, v213
	s_waitcnt lgkmcnt(10)
	v_mfma_f32_16x16x32_bf16 v[2:5], v[74:77], v[166:169], v[2:5]
	v_mfma_f32_16x16x32_bf16 v[34:37], v[90:93], v[166:169], v[34:37]
	ds_read_b64_tr_b16 v[232:233], v148 offset:8192
	ds_read_b64_tr_b16 v[234:235], v148 offset:12288
	v_exp_f32_e32 v214, v214
	v_exp_f32_e32 v215, v215
	s_waitcnt lgkmcnt(10)
	v_mfma_f32_16x16x32_bf16 v[6:9], v[74:77], v[170:173], v[6:9]
	v_mfma_f32_16x16x32_bf16 v[38:41], v[90:93], v[170:173], v[38:41]
	ds_read_b64_tr_b16 v[236:237], v149 offset:8192
	ds_read_b64_tr_b16 v[238:239], v149 offset:12288
	v_exp_f32_e32 v200, v200
	v_exp_f32_e32 v201, v201
	v_exp_f32_e32 v202, v202
	s_waitcnt lgkmcnt(10)
	v_mfma_f32_16x16x32_bf16 v[10:13], v[74:77], v[174:177], v[10:13]
	v_mfma_f32_16x16x32_bf16 v[42:45], v[90:93], v[174:177], v[42:45]
	v_exp_f32_e32 v203, v203
	v_exp_f32_e32 v216, v216
	s_waitcnt lgkmcnt(8)
	v_mfma_f32_16x16x32_bf16 v[14:17], v[74:77], v[178:181], v[14:17]
	v_mfma_f32_16x16x32_bf16 v[46:49], v[90:93], v[178:181], v[46:49]
	v_exp_f32_e32 v217, v217
	v_exp_f32_e32 v218, v218
	s_waitcnt lgkmcnt(6)
	v_mfma_f32_16x16x32_bf16 v[18:21], v[74:77], v[224:227], v[18:21]
	v_mfma_f32_16x16x32_bf16 v[50:53], v[90:93], v[224:227], v[50:53]
	v_exp_f32_e32 v219, v219
	v_exp_f32_e32 v204, v204
	v_exp_f32_e32 v205, v205
	s_waitcnt lgkmcnt(4)
	v_mfma_f32_16x16x32_bf16 v[22:25], v[74:77], v[228:231], v[22:25]
	v_mfma_f32_16x16x32_bf16 v[54:57], v[90:93], v[228:231], v[54:57]
	v_exp_f32_e32 v206, v206
	v_exp_f32_e32 v207, v207
	s_waitcnt lgkmcnt(2)
	v_mfma_f32_16x16x32_bf16 v[26:29], v[74:77], v[232:235], v[26:29]
	v_mfma_f32_16x16x32_bf16 v[58:61], v[90:93], v[232:235], v[58:61]
	v_exp_f32_e32 v220, v220
	v_exp_f32_e32 v221, v221
	s_waitcnt lgkmcnt(0)
	v_mfma_f32_16x16x32_bf16 v[30:33], v[74:77], v[236:239], v[30:33]
	v_mfma_f32_16x16x32_bf16 v[62:65], v[90:93], v[236:239], v[62:65]
	v_exp_f32_e32 v222, v222
	v_exp_f32_e32 v223, v223
	s_waitcnt vmcnt(0)
	s_barrier
	ds_read_b64_tr_b16 v[166:167], v142 offset:32768
	ds_read_b64_tr_b16 v[168:169], v142 offset:36864
	ds_read_b64_tr_b16 v[170:171], v143 offset:32768
	ds_read_b64_tr_b16 v[172:173], v143 offset:36864
	ds_read_b64_tr_b16 v[174:175], v144 offset:32768
	ds_read_b64_tr_b16 v[176:177], v144 offset:36864
	ds_read_b64_tr_b16 v[178:179], v145 offset:32768
	ds_read_b64_tr_b16 v[180:181], v145 offset:36864
	ds_read_b64_tr_b16 v[224:225], v146 offset:32768
	ds_read_b64_tr_b16 v[226:227], v146 offset:36864
	ds_read_b64_tr_b16 v[228:229], v147 offset:32768
	ds_read_b64_tr_b16 v[230:231], v147 offset:36864
	v_add_f32_e32 v130, v192, v193
	v_add_f32_e32 v131, v194, v195
	v_add_f32_e32 v130, v196, v130
	v_add_f32_e32 v131, v197, v131
	v_add_f32_e32 v130, v198, v130
	v_add_f32_e32 v131, v199, v131
	v_add_f32_e32 v130, v200, v130
	v_add_f32_e32 v131, v201, v131
	v_add_f32_e32 v130, v202, v130
	v_add_f32_e32 v131, v203, v131
	v_add_f32_e32 v130, v204, v130
	v_add_f32_e32 v131, v205, v131
	v_add_f32_e32 v130, v206, v130
	v_add_f32_e32 v131, v207, v131
	v_add_f32_e32 v130, v130, v131
	v_add_f32_e32 v165, v165, v130
	v_add_f32_e32 v132, v208, v209
	v_add_f32_e32 v133, v210, v211
	v_add_f32_e32 v132, v212, v132
	v_add_f32_e32 v133, v213, v133
	v_add_f32_e32 v132, v214, v132
	v_add_f32_e32 v133, v215, v133
	v_add_f32_e32 v132, v216, v132
	v_add_f32_e32 v133, v217, v133
	v_add_f32_e32 v132, v218, v132
	v_add_f32_e32 v133, v219, v133
	v_add_f32_e32 v132, v220, v132
	v_add_f32_e32 v133, v221, v133
	v_add_f32_e32 v132, v222, v132
	v_add_f32_e32 v133, v223, v133
	v_add_f32_e32 v132, v132, v133
	v_add_f32_e32 v163, v163, v132
	v_cvt_pk_bf16_f32 v192, v192, v193
	v_cvt_pk_bf16_f32 v193, v194, v195
	v_cvt_pk_bf16_f32 v194, v196, v197
	v_cvt_pk_bf16_f32 v195, v198, v199
	v_cvt_pk_bf16_f32 v200, v200, v201
	v_cvt_pk_bf16_f32 v201, v202, v203
	v_cvt_pk_bf16_f32 v202, v204, v205
	v_cvt_pk_bf16_f32 v203, v206, v207
	v_cvt_pk_bf16_f32 v208, v208, v209
	v_cvt_pk_bf16_f32 v209, v210, v211
	v_cvt_pk_bf16_f32 v210, v212, v213
	v_cvt_pk_bf16_f32 v211, v214, v215
	v_cvt_pk_bf16_f32 v216, v216, v217
	v_cvt_pk_bf16_f32 v217, v218, v219
	v_cvt_pk_bf16_f32 v218, v220, v221
	v_cvt_pk_bf16_f32 v219, v222, v223
	s_waitcnt lgkmcnt(10)
	v_mfma_f32_16x16x32_bf16 v[2:5], v[192:195], v[166:169], v[2:5]
	v_mfma_f32_16x16x32_bf16 v[34:37], v[208:211], v[166:169], v[34:37]
	ds_read_b64_tr_b16 v[232:233], v148 offset:32768
	ds_read_b64_tr_b16 v[234:235], v148 offset:36864
	s_waitcnt lgkmcnt(10)
	v_mfma_f32_16x16x32_bf16 v[6:9], v[192:195], v[170:173], v[6:9]
	v_mfma_f32_16x16x32_bf16 v[38:41], v[208:211], v[170:173], v[38:41]
	ds_read_b64_tr_b16 v[236:237], v149 offset:32768
	ds_read_b64_tr_b16 v[238:239], v149 offset:36864
	s_waitcnt lgkmcnt(10)
	v_mfma_f32_16x16x32_bf16 v[10:13], v[192:195], v[174:177], v[10:13]
	v_mfma_f32_16x16x32_bf16 v[42:45], v[208:211], v[174:177], v[42:45]
	ds_read_b64_tr_b16 v[166:167], v142 offset:40960
	ds_read_b64_tr_b16 v[168:169], v142 offset:45056
	s_waitcnt lgkmcnt(10)
	v_mfma_f32_16x16x32_bf16 v[14:17], v[192:195], v[178:181], v[14:17]
	v_mfma_f32_16x16x32_bf16 v[46:49], v[208:211], v[178:181], v[46:49]
	ds_read_b64_tr_b16 v[170:171], v143 offset:40960
	ds_read_b64_tr_b16 v[172:173], v143 offset:45056
	s_waitcnt lgkmcnt(10)
	v_mfma_f32_16x16x32_bf16 v[18:21], v[192:195], v[224:227], v[18:21]
	v_mfma_f32_16x16x32_bf16 v[50:53], v[208:211], v[224:227], v[50:53]
	ds_read_b64_tr_b16 v[174:175], v144 offset:40960
	ds_read_b64_tr_b16 v[176:177], v144 offset:45056
	s_waitcnt lgkmcnt(10)
	v_mfma_f32_16x16x32_bf16 v[22:25], v[192:195], v[228:231], v[22:25]
	v_mfma_f32_16x16x32_bf16 v[54:57], v[208:211], v[228:231], v[54:57]
	ds_read_b64_tr_b16 v[178:179], v145 offset:40960
	ds_read_b64_tr_b16 v[180:181], v145 offset:45056
	s_waitcnt lgkmcnt(10)
	v_mfma_f32_16x16x32_bf16 v[26:29], v[192:195], v[232:235], v[26:29]
	v_mfma_f32_16x16x32_bf16 v[58:61], v[208:211], v[232:235], v[58:61]
	ds_read_b64_tr_b16 v[224:225], v146 offset:40960
	ds_read_b64_tr_b16 v[226:227], v146 offset:45056
	s_waitcnt lgkmcnt(10)
	v_mfma_f32_16x16x32_bf16 v[30:33], v[192:195], v[236:239], v[30:33]
	v_mfma_f32_16x16x32_bf16 v[62:65], v[208:211], v[236:239], v[62:65]
	ds_read_b64_tr_b16 v[228:229], v147 offset:40960
	ds_read_b64_tr_b16 v[230:231], v147 offset:45056
	s_waitcnt lgkmcnt(10)
	v_mfma_f32_16x16x32_bf16 v[2:5], v[200:203], v[166:169], v[2:5]
	v_mfma_f32_16x16x32_bf16 v[34:37], v[216:219], v[166:169], v[34:37]
	ds_read_b64_tr_b16 v[232:233], v148 offset:40960
	ds_read_b64_tr_b16 v[234:235], v148 offset:45056
	s_waitcnt lgkmcnt(10)
	v_mfma_f32_16x16x32_bf16 v[6:9], v[200:203], v[170:173], v[6:9]
	v_mfma_f32_16x16x32_bf16 v[38:41], v[216:219], v[170:173], v[38:41]
	ds_read_b64_tr_b16 v[236:237], v149 offset:40960
	ds_read_b64_tr_b16 v[238:239], v149 offset:45056
	s_waitcnt lgkmcnt(10)
	v_mfma_f32_16x16x32_bf16 v[10:13], v[200:203], v[174:177], v[10:13]
	v_mfma_f32_16x16x32_bf16 v[42:45], v[216:219], v[174:177], v[42:45]
	s_waitcnt lgkmcnt(8)
	v_mfma_f32_16x16x32_bf16 v[14:17], v[200:203], v[178:181], v[14:17]
	v_mfma_f32_16x16x32_bf16 v[46:49], v[216:219], v[178:181], v[46:49]
	s_waitcnt lgkmcnt(6)
	v_mfma_f32_16x16x32_bf16 v[18:21], v[200:203], v[224:227], v[18:21]
	v_mfma_f32_16x16x32_bf16 v[50:53], v[216:219], v[224:227], v[50:53]
	s_waitcnt lgkmcnt(4)
	v_mfma_f32_16x16x32_bf16 v[22:25], v[200:203], v[228:231], v[22:25]
	v_mfma_f32_16x16x32_bf16 v[54:57], v[216:219], v[228:231], v[54:57]
	s_waitcnt lgkmcnt(2)
	v_mfma_f32_16x16x32_bf16 v[26:29], v[200:203], v[232:235], v[26:29]
	v_mfma_f32_16x16x32_bf16 v[58:61], v[216:219], v[232:235], v[58:61]
	s_waitcnt lgkmcnt(0)
	v_mfma_f32_16x16x32_bf16 v[30:33], v[200:203], v[236:239], v[30:33]
	v_mfma_f32_16x16x32_bf16 v[62:65], v[216:219], v[236:239], v[62:65]
	ds_write_b32 v160, v165
	ds_write_b32 v160, v163 offset:256
	s_waitcnt lgkmcnt(0)
	ds_read_b128 v[66:69], v161 offset:0
	ds_read_b128 v[70:73], v161 offset:64
	ds_read_b128 v[74:77], v161 offset:128
	ds_read_b128 v[78:81], v161 offset:192
	ds_read_b128 v[82:85], v161 offset:256
	ds_read_b128 v[86:89], v161 offset:320
	ds_read_b128 v[90:93], v161 offset:384
	ds_read_b128 v[94:97], v161 offset:448
	s_waitcnt lgkmcnt(0)
	v_add_f32_e32 v66, v66, v70
	v_add_f32_e32 v74, v74, v78
	v_add_f32_e32 v66, v66, v74
	v_rcp_f32_e32 v192, v66
	v_add_f32_e32 v67, v67, v71
	v_add_f32_e32 v75, v75, v79
	v_add_f32_e32 v67, v67, v75
	v_rcp_f32_e32 v193, v67
	v_add_f32_e32 v68, v68, v72
	v_add_f32_e32 v76, v76, v80
	v_add_f32_e32 v68, v68, v76
	v_rcp_f32_e32 v194, v68
	v_add_f32_e32 v69, v69, v73
	v_add_f32_e32 v77, v77, v81
	v_add_f32_e32 v69, v69, v77
	v_rcp_f32_e32 v195, v69
	v_add_f32_e32 v82, v82, v86
	v_add_f32_e32 v90, v90, v94
	v_add_f32_e32 v82, v82, v90
	v_rcp_f32_e32 v196, v82
	v_add_f32_e32 v83, v83, v87
	v_add_f32_e32 v91, v91, v95
	v_add_f32_e32 v83, v83, v91
	v_rcp_f32_e32 v197, v83
	v_add_f32_e32 v84, v84, v88
	v_add_f32_e32 v92, v92, v96
	v_add_f32_e32 v84, v84, v92
	v_rcp_f32_e32 v198, v84
	v_add_f32_e32 v85, v85, v89
	v_add_f32_e32 v93, v93, v97
	v_add_f32_e32 v85, v85, v93
	v_rcp_f32_e32 v199, v85
	s_nop 0
	v_mul_f32_e32 v2, v2, v192
	v_mul_f32_e32 v6, v6, v192
	v_cvt_pk_bf16_f32 v200, v2, v6
	global_store_short v156, v200, s[46:47] offset:0
	global_store_short_d16_hi v156, v200, s[46:47] offset:32
	v_mul_f32_e32 v10, v10, v192
	v_mul_f32_e32 v14, v14, v192
	v_cvt_pk_bf16_f32 v201, v10, v14
	global_store_short v156, v201, s[46:47] offset:64
	global_store_short_d16_hi v156, v201, s[46:47] offset:96
	v_mul_f32_e32 v18, v18, v192
	v_mul_f32_e32 v22, v22, v192
	v_cvt_pk_bf16_f32 v202, v18, v22
	global_store_short v156, v202, s[46:47] offset:128
	global_store_short_d16_hi v156, v202, s[46:47] offset:160
	v_mul_f32_e32 v26, v26, v192
	v_mul_f32_e32 v30, v30, v192
	v_cvt_pk_bf16_f32 v203, v26, v30
	global_store_short v156, v203, s[46:47] offset:192
	global_store_short_d16_hi v156, v203, s[46:47] offset:224
	v_mul_f32_e32 v3, v3, v193
	v_mul_f32_e32 v7, v7, v193
	v_cvt_pk_bf16_f32 v204, v3, v7
	global_store_short v156, v204, s[46:47] offset:2048
	global_store_short_d16_hi v156, v204, s[46:47] offset:2080
	v_mul_f32_e32 v11, v11, v193
	v_mul_f32_e32 v15, v15, v193
	v_cvt_pk_bf16_f32 v205, v11, v15
	global_store_short v156, v205, s[46:47] offset:2112
	global_store_short_d16_hi v156, v205, s[46:47] offset:2144
	v_mul_f32_e32 v19, v19, v193
	v_mul_f32_e32 v23, v23, v193
	v_cvt_pk_bf16_f32 v206, v19, v23
	global_store_short v156, v206, s[46:47] offset:2176
	global_store_short_d16_hi v156, v206, s[46:47] offset:2208
	v_mul_f32_e32 v27, v27, v193
	v_mul_f32_e32 v31, v31, v193
	v_cvt_pk_bf16_f32 v207, v27, v31
	global_store_short v156, v207, s[46:47] offset:2240
	global_store_short_d16_hi v156, v207, s[46:47] offset:2272
	v_mul_f32_e32 v4, v4, v194
	v_mul_f32_e32 v8, v8, v194
	v_cvt_pk_bf16_f32 v200, v4, v8
	global_store_short v157, v200, s[46:47] offset:0
	global_store_short_d16_hi v157, v200, s[46:47] offset:32
	v_mul_f32_e32 v12, v12, v194
	v_mul_f32_e32 v16, v16, v194
	v_cvt_pk_bf16_f32 v201, v12, v16
	global_store_short v157, v201, s[46:47] offset:64
	global_store_short_d16_hi v157, v201, s[46:47] offset:96
	v_mul_f32_e32 v20, v20, v194
	v_mul_f32_e32 v24, v24, v194
	v_cvt_pk_bf16_f32 v202, v20, v24
	global_store_short v157, v202, s[46:47] offset:128
	global_store_short_d16_hi v157, v202, s[46:47] offset:160
	v_mul_f32_e32 v28, v28, v194
	v_mul_f32_e32 v32, v32, v194
	v_cvt_pk_bf16_f32 v203, v28, v32
	global_store_short v157, v203, s[46:47] offset:192
	global_store_short_d16_hi v157, v203, s[46:47] offset:224
	v_mul_f32_e32 v5, v5, v195
	v_mul_f32_e32 v9, v9, v195
	v_cvt_pk_bf16_f32 v204, v5, v9
	global_store_short v157, v204, s[46:47] offset:2048
	global_store_short_d16_hi v157, v204, s[46:47] offset:2080
	v_mul_f32_e32 v13, v13, v195
	v_mul_f32_e32 v17, v17, v195
	v_cvt_pk_bf16_f32 v205, v13, v17
	global_store_short v157, v205, s[46:47] offset:2112
	global_store_short_d16_hi v157, v205, s[46:47] offset:2144
	v_mul_f32_e32 v21, v21, v195
	v_mul_f32_e32 v25, v25, v195
	v_cvt_pk_bf16_f32 v206, v21, v25
	global_store_short v157, v206, s[46:47] offset:2176
	global_store_short_d16_hi v157, v206, s[46:47] offset:2208
	v_mul_f32_e32 v29, v29, v195
	v_mul_f32_e32 v33, v33, v195
	v_cvt_pk_bf16_f32 v207, v29, v33
	global_store_short v157, v207, s[46:47] offset:2240
	global_store_short_d16_hi v157, v207, s[46:47] offset:2272
	v_mul_f32_e32 v34, v34, v196
	v_mul_f32_e32 v38, v38, v196
	v_cvt_pk_bf16_f32 v200, v34, v38
	global_store_short v158, v200, s[46:47] offset:0
	global_store_short_d16_hi v158, v200, s[46:47] offset:32
	v_mul_f32_e32 v42, v42, v196
	v_mul_f32_e32 v46, v46, v196
	v_cvt_pk_bf16_f32 v201, v42, v46
	global_store_short v158, v201, s[46:47] offset:64
	global_store_short_d16_hi v158, v201, s[46:47] offset:96
	v_mul_f32_e32 v50, v50, v196
	v_mul_f32_e32 v54, v54, v196
	v_cvt_pk_bf16_f32 v202, v50, v54
	global_store_short v158, v202, s[46:47] offset:128
	global_store_short_d16_hi v158, v202, s[46:47] offset:160
	v_mul_f32_e32 v58, v58, v196
	v_mul_f32_e32 v62, v62, v196
	v_cvt_pk_bf16_f32 v203, v58, v62
	global_store_short v158, v203, s[46:47] offset:192
	global_store_short_d16_hi v158, v203, s[46:47] offset:224
	v_mul_f32_e32 v35, v35, v197
	v_mul_f32_e32 v39, v39, v197
	v_cvt_pk_bf16_f32 v204, v35, v39
	global_store_short v158, v204, s[46:47] offset:2048
	global_store_short_d16_hi v158, v204, s[46:47] offset:2080
	v_mul_f32_e32 v43, v43, v197
	v_mul_f32_e32 v47, v47, v197
	v_cvt_pk_bf16_f32 v205, v43, v47
	global_store_short v158, v205, s[46:47] offset:2112
	global_store_short_d16_hi v158, v205, s[46:47] offset:2144
	v_mul_f32_e32 v51, v51, v197
	v_mul_f32_e32 v55, v55, v197
	v_cvt_pk_bf16_f32 v206, v51, v55
	global_store_short v158, v206, s[46:47] offset:2176
	global_store_short_d16_hi v158, v206, s[46:47] offset:2208
	v_mul_f32_e32 v59, v59, v197
	v_mul_f32_e32 v63, v63, v197
	v_cvt_pk_bf16_f32 v207, v59, v63
	global_store_short v158, v207, s[46:47] offset:2240
	global_store_short_d16_hi v158, v207, s[46:47] offset:2272
	v_mul_f32_e32 v36, v36, v198
	v_mul_f32_e32 v40, v40, v198
	v_cvt_pk_bf16_f32 v200, v36, v40
	global_store_short v159, v200, s[46:47] offset:0
	global_store_short_d16_hi v159, v200, s[46:47] offset:32
	v_mul_f32_e32 v44, v44, v198
	v_mul_f32_e32 v48, v48, v198
	v_cvt_pk_bf16_f32 v201, v44, v48
	global_store_short v159, v201, s[46:47] offset:64
	global_store_short_d16_hi v159, v201, s[46:47] offset:96
	v_mul_f32_e32 v52, v52, v198
	v_mul_f32_e32 v56, v56, v198
	v_cvt_pk_bf16_f32 v202, v52, v56
	global_store_short v159, v202, s[46:47] offset:128
	global_store_short_d16_hi v159, v202, s[46:47] offset:160
	v_mul_f32_e32 v60, v60, v198
	v_mul_f32_e32 v64, v64, v198
	v_cvt_pk_bf16_f32 v203, v60, v64
	global_store_short v159, v203, s[46:47] offset:192
	global_store_short_d16_hi v159, v203, s[46:47] offset:224
	v_mul_f32_e32 v37, v37, v199
	v_mul_f32_e32 v41, v41, v199
	v_cvt_pk_bf16_f32 v204, v37, v41
	global_store_short v159, v204, s[46:47] offset:2048
	global_store_short_d16_hi v159, v204, s[46:47] offset:2080
	v_mul_f32_e32 v45, v45, v199
	v_mul_f32_e32 v49, v49, v199
	v_cvt_pk_bf16_f32 v205, v45, v49
	global_store_short v159, v205, s[46:47] offset:2112
	global_store_short_d16_hi v159, v205, s[46:47] offset:2144
	v_mul_f32_e32 v53, v53, v199
	v_mul_f32_e32 v57, v57, v199
	v_cvt_pk_bf16_f32 v206, v53, v57
	global_store_short v159, v206, s[46:47] offset:2176
	global_store_short_d16_hi v159, v206, s[46:47] offset:2208
	v_mul_f32_e32 v61, v61, v199
	v_mul_f32_e32 v65, v65, v199
	v_cvt_pk_bf16_f32 v207, v61, v65
	global_store_short v159, v207, s[46:47] offset:2240
	global_store_short_d16_hi v159, v207, s[46:47] offset:2272
	s_add_i32 s3, s3, s33
	s_cmpk_lt_i32 s3, 0x400
	s_barrier
	s_cbranch_scc1 .LBB0_419
